# hand-written GEMM epilogues (modes 1,2,3) re-encoded e64 and padded so every 8-byte instruction is 8-byte aligned, on the aligned-scan version
# speedup vs baseline: 1.0180x; 1.0180x over previous
.LBB0_141:
	s_add_i32 s72, s40, 2
	s_add_u32 s68, s0, 0x80
	s_addc_u32 s41, s1, 0
	s_add_i32 s73, 0, 0x10000
	v_add_u32_e32 v140, s73, v183
	ds_read_b128 v[128:131], v140
	ds_read_b128 v[132:135], v140 offset:1024
	ds_read_b128 v[136:139], v140 offset:2048
	ds_read_b128 v[140:143], v140 offset:3072
	s_cmp_eq_u32 s10, s40
	s_cselect_b32 s40, s64, s68
	s_cselect_b32 s41, s65, s41
	s_cselect_b32 s69, s67, s71
	s_cselect_b32 s68, s66, s70
	v_lshl_add_u64 v[176:177], s[0:1], 0, v[192:193]
	s_add_i32 m0, s76, 0xc000
	ds_read_b128 v[144:147], v239
	ds_read_b128 v[148:151], v239 offset:1024
	ds_read_b128 v[152:155], v239 offset:2048
	ds_read_b128 v[156:159], v239 offset:3072
	ds_read_b128 v[160:163], v239 offset:4096
	ds_read_b128 v[164:167], v239 offset:5120
	ds_read_b128 v[168:171], v239 offset:6144
	ds_read_b128 v[172:175], v239 offset:7168
	global_load_lds_dwordx4 v[176:177], off
	v_lshl_add_u64 v[176:177], s[0:1], 0, v[194:195]
	s_add_i32 m0, s76, 0xe000
	s_nop 0
	global_load_lds_dwordx4 v[176:177], off
	s_waitcnt lgkmcnt(8)
	s_barrier
	s_waitcnt lgkmcnt(0)
	s_waitcnt lgkmcnt(0)
	v_mfma_f32_16x16x32_bf16 v[124:127], v[128:131], v[144:147], v[124:127]
	v_mfma_f32_16x16x32_bf16 v[116:119], v[136:139], v[144:147], v[116:119]
	v_mfma_f32_16x16x32_bf16 v[108:111], v[128:131], v[152:155], v[108:111]
	v_mfma_f32_16x16x32_bf16 v[100:103], v[136:139], v[152:155], v[100:103]
	v_mfma_f32_16x16x32_bf16 v[92:95], v[128:131], v[160:163], v[92:95]
	v_mfma_f32_16x16x32_bf16 v[84:87], v[136:139], v[160:163], v[84:87]
	v_mfma_f32_16x16x32_bf16 v[76:79], v[128:131], v[168:171], v[76:79]
	v_mfma_f32_16x16x32_bf16 v[68:71], v[136:139], v[168:171], v[68:71]
	v_mfma_f32_16x16x32_bf16 v[124:127], v[132:135], v[148:151], v[124:127]
	v_mfma_f32_16x16x32_bf16 v[116:119], v[140:143], v[148:151], v[116:119]
	v_mfma_f32_16x16x32_bf16 v[108:111], v[132:135], v[156:159], v[108:111]
	v_mfma_f32_16x16x32_bf16 v[100:103], v[140:143], v[156:159], v[100:103]
	v_mfma_f32_16x16x32_bf16 v[92:95], v[132:135], v[164:167], v[92:95]
	v_mfma_f32_16x16x32_bf16 v[84:87], v[140:143], v[164:167], v[84:87]
	v_mfma_f32_16x16x32_bf16 v[76:79], v[132:135], v[172:175], v[76:79]
	v_mfma_f32_16x16x32_bf16 v[68:71], v[140:143], v[172:175], v[68:71]
	s_barrier
	s_add_i32 s80, 0, 0x14000
	s_add_i32 s73, s73, s33
	v_add_u32_e32 v204, s80, v183
	v_lshl_add_u64 v[208:209], s[68:69], 0, v[186:187]
	s_mov_b32 m0, s73
	ds_read_b128 v[176:179], v204
	ds_read_b128 v[196:199], v204 offset:1024
	ds_read_b128 v[200:203], v204 offset:2048
	ds_read_b128 v[204:207], v204 offset:3072
	global_load_lds_dwordx4 v[208:209], off
	v_lshl_add_u64 v[210:211], s[68:69], 0, v[190:191]
	s_add_i32 m0, s73, 0x2000
	s_nop 0
	global_load_lds_dwordx4 v[210:211], off
	s_barrier
	s_waitcnt lgkmcnt(0)
	s_waitcnt lgkmcnt(0)
	v_mfma_f32_16x16x32_bf16 v[120:123], v[176:179], v[144:147], v[120:123]
	v_mfma_f32_16x16x32_bf16 v[112:115], v[200:203], v[144:147], v[112:115]
	v_mfma_f32_16x16x32_bf16 v[104:107], v[176:179], v[152:155], v[104:107]
	v_mfma_f32_16x16x32_bf16 v[96:99], v[200:203], v[152:155], v[96:99]
	v_mfma_f32_16x16x32_bf16 v[88:91], v[176:179], v[160:163], v[88:91]
	v_mfma_f32_16x16x32_bf16 v[80:83], v[200:203], v[160:163], v[80:83]
	v_mfma_f32_16x16x32_bf16 v[72:75], v[176:179], v[168:171], v[72:75]
	v_mfma_f32_16x16x32_bf16 v[64:67], v[200:203], v[168:171], v[64:67]
	v_mfma_f32_16x16x32_bf16 v[120:123], v[196:199], v[148:151], v[120:123]
	v_mfma_f32_16x16x32_bf16 v[112:115], v[204:207], v[148:151], v[112:115]
	v_mfma_f32_16x16x32_bf16 v[104:107], v[196:199], v[156:159], v[104:107]
	v_mfma_f32_16x16x32_bf16 v[96:99], v[204:207], v[156:159], v[96:99]
	v_mfma_f32_16x16x32_bf16 v[88:91], v[196:199], v[164:167], v[88:91]
	v_mfma_f32_16x16x32_bf16 v[80:83], v[204:207], v[164:167], v[80:83]
	v_mfma_f32_16x16x32_bf16 v[72:75], v[196:199], v[172:175], v[72:75]
	v_mfma_f32_16x16x32_bf16 v[64:67], v[204:207], v[172:175], v[64:67]
	s_mov_b32 m0, s76
	v_lshl_add_u64 v[212:213], s[40:41], 0, v[184:185]
	s_barrier
	ds_read_b128 v[144:147], v239 offset:16384
	ds_read_b128 v[148:151], v239 offset:17408
	ds_read_b128 v[152:155], v239 offset:18432
	ds_read_b128 v[156:159], v239 offset:19456
	ds_read_b128 v[160:163], v239 offset:20480
	ds_read_b128 v[164:167], v239 offset:21504
	ds_read_b128 v[168:171], v239 offset:22528
	ds_read_b128 v[172:175], v239 offset:23552
	global_load_lds_dwordx4 v[212:213], off
	v_lshl_add_u64 v[214:215], s[40:41], 0, v[188:189]
	s_mov_b32 m0, s4
	s_nop 0
	global_load_lds_dwordx4 v[214:215], off
	s_barrier
	s_waitcnt lgkmcnt(0)
	s_waitcnt lgkmcnt(0)
	v_mfma_f32_16x16x32_bf16 v[60:63], v[128:131], v[144:147], v[60:63]
	v_mfma_f32_16x16x32_bf16 v[52:55], v[136:139], v[144:147], v[52:55]
	v_mfma_f32_16x16x32_bf16 v[44:47], v[128:131], v[152:155], v[44:47]
	v_mfma_f32_16x16x32_bf16 v[36:39], v[136:139], v[152:155], v[36:39]
	v_mfma_f32_16x16x32_bf16 v[28:31], v[128:131], v[160:163], v[28:31]
	v_mfma_f32_16x16x32_bf16 v[20:23], v[136:139], v[160:163], v[20:23]
	v_mfma_f32_16x16x32_bf16 v[12:15], v[128:131], v[168:171], v[12:15]
	v_mfma_f32_16x16x32_bf16 v[4:7], v[136:139], v[168:171], v[4:7]
	v_mfma_f32_16x16x32_bf16 v[60:63], v[132:135], v[148:151], v[60:63]
	v_mfma_f32_16x16x32_bf16 v[52:55], v[140:143], v[148:151], v[52:55]
	v_mfma_f32_16x16x32_bf16 v[44:47], v[132:135], v[156:159], v[44:47]
	v_mfma_f32_16x16x32_bf16 v[36:39], v[140:143], v[156:159], v[36:39]
	v_mfma_f32_16x16x32_bf16 v[28:31], v[132:135], v[164:167], v[28:31]
	v_mfma_f32_16x16x32_bf16 v[20:23], v[140:143], v[164:167], v[20:23]
	v_mfma_f32_16x16x32_bf16 v[12:15], v[132:135], v[172:175], v[12:15]
	v_mfma_f32_16x16x32_bf16 v[4:7], v[140:143], v[172:175], v[4:7]
	s_barrier
	s_add_u32 s68, s68, s98
	s_addc_u32 s69, s69, 0
	s_add_i32 s73, s80, s33
	v_lshl_add_u64 v[216:217], s[68:69], 0, v[186:187]
	s_mov_b32 m0, s73
	v_lshl_add_u64 v[218:219], s[68:69], 0, v[190:191]
	global_load_lds_dwordx4 v[216:217], off
	s_add_i32 m0, s73, 0x2000
	s_nop 0
	global_load_lds_dwordx4 v[218:219], off
	s_waitcnt vmcnt(6)
	s_barrier
	v_mfma_f32_16x16x32_bf16 v[56:59], v[176:179], v[144:147], v[56:59]
	v_mfma_f32_16x16x32_bf16 v[48:51], v[200:203], v[144:147], v[48:51]
	v_mfma_f32_16x16x32_bf16 v[40:43], v[176:179], v[152:155], v[40:43]
	v_mfma_f32_16x16x32_bf16 v[32:35], v[200:203], v[152:155], v[32:35]
	v_mfma_f32_16x16x32_bf16 v[24:27], v[176:179], v[160:163], v[24:27]
	v_mfma_f32_16x16x32_bf16 v[16:19], v[200:203], v[160:163], v[16:19]
	v_mfma_f32_16x16x32_bf16 v[8:11], v[176:179], v[168:171], v[8:11]
	v_mfma_f32_16x16x32_bf16 v[0:3], v[200:203], v[168:171], v[0:3]
	v_mfma_f32_16x16x32_bf16 v[56:59], v[196:199], v[148:151], v[56:59]
	v_mfma_f32_16x16x32_bf16 v[48:51], v[204:207], v[148:151], v[48:51]
	v_mfma_f32_16x16x32_bf16 v[40:43], v[196:199], v[156:159], v[40:43]
	v_mfma_f32_16x16x32_bf16 v[32:35], v[204:207], v[156:159], v[32:35]
	v_mfma_f32_16x16x32_bf16 v[24:27], v[196:199], v[164:167], v[24:27]
	v_mfma_f32_16x16x32_bf16 v[16:19], v[204:207], v[164:167], v[16:19]
	v_mfma_f32_16x16x32_bf16 v[8:11], v[196:199], v[172:175], v[8:11]
	v_mfma_f32_16x16x32_bf16 v[0:3], v[204:207], v[172:175], v[0:3]
	s_add_i32 s68, 0, 0x18000
	v_add_u32_e32 v140, s68, v183
	s_barrier
	ds_read_b128 v[128:131], v140
	ds_read_b128 v[132:135], v140 offset:1024
	ds_read_b128 v[136:139], v140 offset:2048
	ds_read_b128 v[140:143], v140 offset:3072
	s_add_u32 s40, s40, s98
	s_addc_u32 s41, s41, 0
	s_mov_b32 m0, s5
	v_lshl_add_u64 v[176:177], s[40:41], 0, v[184:185]
	ds_read_b128 v[144:147], v239 offset:32768
	ds_read_b128 v[148:151], v239 offset:33792
	ds_read_b128 v[152:155], v239 offset:34816
	ds_read_b128 v[156:159], v239 offset:35840
	ds_read_b128 v[160:163], v239 offset:36864
	ds_read_b128 v[164:167], v239 offset:37888
	ds_read_b128 v[168:171], v239 offset:38912
	ds_read_b128 v[172:175], v239 offset:39936
	global_load_lds_dwordx4 v[176:177], off
	v_lshl_add_u64 v[176:177], s[40:41], 0, v[188:189]
	s_mov_b32 m0, s6
	s_nop 0
	global_load_lds_dwordx4 v[176:177], off
	s_waitcnt lgkmcnt(8)
	s_barrier
	s_waitcnt lgkmcnt(0)
	s_waitcnt lgkmcnt(0)
	v_mfma_f32_16x16x32_bf16 v[124:127], v[128:131], v[144:147], v[124:127]
	v_mfma_f32_16x16x32_bf16 v[116:119], v[136:139], v[144:147], v[116:119]
	v_mfma_f32_16x16x32_bf16 v[108:111], v[128:131], v[152:155], v[108:111]
	v_mfma_f32_16x16x32_bf16 v[100:103], v[136:139], v[152:155], v[100:103]
	v_mfma_f32_16x16x32_bf16 v[92:95], v[128:131], v[160:163], v[92:95]
	v_mfma_f32_16x16x32_bf16 v[84:87], v[136:139], v[160:163], v[84:87]
	v_mfma_f32_16x16x32_bf16 v[76:79], v[128:131], v[168:171], v[76:79]
	v_mfma_f32_16x16x32_bf16 v[68:71], v[136:139], v[168:171], v[68:71]
	v_mfma_f32_16x16x32_bf16 v[124:127], v[132:135], v[148:151], v[124:127]
	v_mfma_f32_16x16x32_bf16 v[116:119], v[140:143], v[148:151], v[116:119]
	v_mfma_f32_16x16x32_bf16 v[108:111], v[132:135], v[156:159], v[108:111]
	v_mfma_f32_16x16x32_bf16 v[100:103], v[140:143], v[156:159], v[100:103]
	v_mfma_f32_16x16x32_bf16 v[92:95], v[132:135], v[164:167], v[92:95]
	v_mfma_f32_16x16x32_bf16 v[84:87], v[140:143], v[164:167], v[84:87]
	v_mfma_f32_16x16x32_bf16 v[76:79], v[132:135], v[172:175], v[76:79]
	v_mfma_f32_16x16x32_bf16 v[68:71], v[140:143], v[172:175], v[68:71]
	s_barrier
	s_add_i32 s40, 0, 0x1c000
	s_add_i32 s41, s68, s33
	v_add_u32_e32 v204, s40, v183
	v_lshl_add_u64 v[208:209], v[208:209], 0, s[96:97]
	s_mov_b32 m0, s41
	ds_read_b128 v[176:179], v204
	ds_read_b128 v[196:199], v204 offset:1024
	ds_read_b128 v[200:203], v204 offset:2048
	ds_read_b128 v[204:207], v204 offset:3072
	global_load_lds_dwordx4 v[208:209], off
	v_lshl_add_u64 v[208:209], v[210:211], 0, s[96:97]
	s_add_i32 m0, s41, 0x2000
	s_nop 0
	global_load_lds_dwordx4 v[208:209], off
	s_barrier
	s_waitcnt lgkmcnt(0)
	s_waitcnt lgkmcnt(0)
	v_mfma_f32_16x16x32_bf16 v[120:123], v[176:179], v[144:147], v[120:123]
	v_mfma_f32_16x16x32_bf16 v[112:115], v[200:203], v[144:147], v[112:115]
	v_mfma_f32_16x16x32_bf16 v[104:107], v[176:179], v[152:155], v[104:107]
	v_mfma_f32_16x16x32_bf16 v[96:99], v[200:203], v[152:155], v[96:99]
	v_mfma_f32_16x16x32_bf16 v[88:91], v[176:179], v[160:163], v[88:91]
	v_mfma_f32_16x16x32_bf16 v[80:83], v[200:203], v[160:163], v[80:83]
	v_mfma_f32_16x16x32_bf16 v[72:75], v[176:179], v[168:171], v[72:75]
	v_mfma_f32_16x16x32_bf16 v[64:67], v[200:203], v[168:171], v[64:67]
	v_mfma_f32_16x16x32_bf16 v[120:123], v[196:199], v[148:151], v[120:123]
	v_mfma_f32_16x16x32_bf16 v[112:115], v[204:207], v[148:151], v[112:115]
	v_mfma_f32_16x16x32_bf16 v[104:107], v[196:199], v[156:159], v[104:107]
	v_mfma_f32_16x16x32_bf16 v[96:99], v[204:207], v[156:159], v[96:99]
	v_mfma_f32_16x16x32_bf16 v[88:91], v[196:199], v[164:167], v[88:91]
	v_mfma_f32_16x16x32_bf16 v[80:83], v[204:207], v[164:167], v[80:83]
	v_mfma_f32_16x16x32_bf16 v[72:75], v[196:199], v[172:175], v[72:75]
	v_mfma_f32_16x16x32_bf16 v[64:67], v[204:207], v[172:175], v[64:67]
	s_mov_b32 m0, s8
	v_lshl_add_u64 v[208:209], v[212:213], 0, s[96:97]
	s_barrier
	ds_read_b128 v[144:147], v239 offset:49152
	ds_read_b128 v[148:151], v239 offset:50176
	ds_read_b128 v[152:155], v239 offset:51200
	ds_read_b128 v[156:159], v239 offset:52224
	ds_read_b128 v[160:163], v239 offset:53248
	ds_read_b128 v[164:167], v239 offset:54272
	ds_read_b128 v[168:171], v239 offset:55296
	ds_read_b128 v[172:175], v239 offset:56320
	global_load_lds_dwordx4 v[208:209], off
	v_lshl_add_u64 v[208:209], v[214:215], 0, s[96:97]
	s_mov_b32 m0, s9
	s_nop 0
	global_load_lds_dwordx4 v[208:209], off
	s_barrier
	s_waitcnt lgkmcnt(0)
	s_waitcnt lgkmcnt(0)
	v_mfma_f32_16x16x32_bf16 v[60:63], v[128:131], v[144:147], v[60:63]
	v_mfma_f32_16x16x32_bf16 v[52:55], v[136:139], v[144:147], v[52:55]
	v_mfma_f32_16x16x32_bf16 v[44:47], v[128:131], v[152:155], v[44:47]
	v_mfma_f32_16x16x32_bf16 v[36:39], v[136:139], v[152:155], v[36:39]
	v_mfma_f32_16x16x32_bf16 v[28:31], v[128:131], v[160:163], v[28:31]
	v_mfma_f32_16x16x32_bf16 v[20:23], v[136:139], v[160:163], v[20:23]
	v_mfma_f32_16x16x32_bf16 v[12:15], v[128:131], v[168:171], v[12:15]
	v_mfma_f32_16x16x32_bf16 v[4:7], v[136:139], v[168:171], v[4:7]
	v_mfma_f32_16x16x32_bf16 v[60:63], v[132:135], v[148:151], v[60:63]
	v_mfma_f32_16x16x32_bf16 v[52:55], v[140:143], v[148:151], v[52:55]
	v_mfma_f32_16x16x32_bf16 v[44:47], v[132:135], v[156:159], v[44:47]
	v_mfma_f32_16x16x32_bf16 v[36:39], v[140:143], v[156:159], v[36:39]
	v_mfma_f32_16x16x32_bf16 v[28:31], v[132:135], v[164:167], v[28:31]
	v_mfma_f32_16x16x32_bf16 v[20:23], v[140:143], v[164:167], v[20:23]
	v_mfma_f32_16x16x32_bf16 v[12:15], v[132:135], v[172:175], v[12:15]
	v_mfma_f32_16x16x32_bf16 v[4:7], v[140:143], v[172:175], v[4:7]
	s_barrier
	s_add_i32 s40, s40, s33
	v_lshl_add_u64 v[128:129], v[216:217], 0, s[96:97]
	s_mov_b32 m0, s40
	s_nop 0
	global_load_lds_dwordx4 v[128:129], off
	v_lshl_add_u64 v[128:129], v[218:219], 0, s[96:97]
	s_add_i32 m0, s40, 0x2000
	s_nop 0
	global_load_lds_dwordx4 v[128:129], off
	s_waitcnt vmcnt(6)
	s_barrier
	v_mfma_f32_16x16x32_bf16 v[56:59], v[176:179], v[144:147], v[56:59]
	v_mfma_f32_16x16x32_bf16 v[48:51], v[200:203], v[144:147], v[48:51]
	v_mfma_f32_16x16x32_bf16 v[40:43], v[176:179], v[152:155], v[40:43]
	v_mfma_f32_16x16x32_bf16 v[32:35], v[200:203], v[152:155], v[32:35]
	v_mfma_f32_16x16x32_bf16 v[24:27], v[176:179], v[160:163], v[24:27]
	v_mfma_f32_16x16x32_bf16 v[16:19], v[200:203], v[160:163], v[16:19]
	v_mfma_f32_16x16x32_bf16 v[8:11], v[176:179], v[168:171], v[8:11]
	v_mfma_f32_16x16x32_bf16 v[0:3], v[200:203], v[168:171], v[0:3]
	v_mfma_f32_16x16x32_bf16 v[56:59], v[196:199], v[148:151], v[56:59]
	v_mfma_f32_16x16x32_bf16 v[48:51], v[204:207], v[148:151], v[48:51]
	v_mfma_f32_16x16x32_bf16 v[40:43], v[196:199], v[156:159], v[40:43]
	v_mfma_f32_16x16x32_bf16 v[32:35], v[204:207], v[156:159], v[32:35]
	v_mfma_f32_16x16x32_bf16 v[24:27], v[196:199], v[164:167], v[24:27]
	v_mfma_f32_16x16x32_bf16 v[16:19], v[204:207], v[164:167], v[16:19]
	v_mfma_f32_16x16x32_bf16 v[8:11], v[196:199], v[172:175], v[8:11]
	v_mfma_f32_16x16x32_bf16 v[0:3], v[204:207], v[172:175], v[0:3]
	s_add_u32 s0, s0, 0x100
	s_addc_u32 s1, s1, 0
	s_add_u32 s70, s70, 0x100
	s_addc_u32 s71, s71, 0
	s_cmp_ge_u32 s72, s7
	s_mov_b32 s40, s72
	s_barrier
	s_cbranch_scc0 .LBB0_141
	v_lshl_add_u32 v196, s19, 8, v181
	s_cmp_lt_i32 s78, 2
	s_mov_b64 s[0:1], -1
	s_cbranch_scc1 .LBB0_223
	s_cmp_gt_i32 s78, 2
	s_cbranch_scc0 .LBB0_220
	s_lshl_b32 s0, s18, 8
	s_ashr_i32 s68, s18, 1
	s_nop 0
	s_and_b32 s0, s0, 0x100
	v_or_b32_e64 v147, s0, v238
	s_lshl_b32 s72, s68, 25
	s_nop 0
	v_lshl_add_u32 v146, v196, 9, v147
	v_lshlrev_b32_e64 v146, 1, v146
	v_add_u32_e64 v146, s72, v146
	s_cmp_gt_i32 s68, 3
	s_cbranch_scc1 .Lepi3_plain
	v_readlane_b32 s40, v241, 10
	v_readlane_b32 s41, v241, 11
	v_readlane_b32 s70, v241, 14
	v_readlane_b32 s71, v241, 15
	v_lshlrev_b32_e64 v147, 2, v147
	v_mov_b32_e32 v144, 0xbfb8aa3b
	s_lshl_b32 s69, s68, 11
	s_nop 3
	s_cmp_lt_i32 s68, 2
	s_cselect_b64 s[0:1], -1, 0
	s_cselect_b32 s40, s40, s70
	s_cselect_b32 s41, s41, s71
	s_cselect_b32 s72, 0, 0x1000
	s_sub_u32 s69, s69, s72
	s_add_u32 s40, s40, s69
	s_addc_u32 s41, s41, 0
	s_nop 0
	v_cndmask_b32_e64 v158, 1.0, v235, s[0:1]
	global_load_dwordx4 v[128:131], v147, s[40:41]
	global_load_dwordx4 v[132:135], v147, s[40:41] offset:16
	global_load_dwordx4 v[136:139], v147, s[40:41] offset:512
	global_load_dwordx4 v[140:143], v147, s[40:41] offset:528
	s_waitcnt vmcnt(0)
	s_nop 0
	v_pk_add_f32 v[124:125], v[124:125], v[128:129]
	v_pk_add_f32 v[126:127], v[126:127], v[130:131]
	v_pk_add_f32 v[116:117], v[116:117], v[132:133]
	v_pk_add_f32 v[118:119], v[118:119], v[134:135]
	v_pk_mul_f32 v[124:125], v[124:125], v[144:145] op_sel_hi:[1,0]
	v_pk_mul_f32 v[126:127], v[126:127], v[144:145] op_sel_hi:[1,0]
	v_pk_mul_f32 v[116:117], v[116:117], v[144:145] op_sel_hi:[1,0]
	v_pk_mul_f32 v[118:119], v[118:119], v[144:145] op_sel_hi:[1,0]
	v_exp_f32_e64 v124, v124
	v_exp_f32_e64 v125, v125
	v_exp_f32_e64 v126, v126
	v_exp_f32_e64 v127, v127
	v_exp_f32_e64 v116, v116
	v_exp_f32_e64 v117, v117
	v_exp_f32_e64 v118, v118
	v_exp_f32_e64 v119, v119
	v_pk_add_f32 v[124:125], v[124:125], 1.0 op_sel_hi:[1,0]
	v_pk_add_f32 v[126:127], v[126:127], 1.0 op_sel_hi:[1,0]
	v_pk_add_f32 v[116:117], v[116:117], 1.0 op_sel_hi:[1,0]
	v_pk_add_f32 v[118:119], v[118:119], 1.0 op_sel_hi:[1,0]
	v_rcp_f32_e64 v124, v124
	v_rcp_f32_e64 v125, v125
	v_rcp_f32_e64 v126, v126
	v_rcp_f32_e64 v127, v127
	v_rcp_f32_e64 v116, v116
	v_rcp_f32_e64 v117, v117
	v_rcp_f32_e64 v118, v118
	v_rcp_f32_e64 v119, v119
	v_pk_mul_f32 v[124:125], v[124:125], v[158:159] op_sel_hi:[1,0]
	v_pk_mul_f32 v[126:127], v[126:127], v[158:159] op_sel_hi:[1,0]
	v_pk_mul_f32 v[116:117], v[116:117], v[158:159] op_sel_hi:[1,0]
	v_pk_mul_f32 v[118:119], v[118:119], v[158:159] op_sel_hi:[1,0]
	v_cvt_pk_f16_f32 v148, v124, v125
	v_cvt_pk_f16_f32 v149, v126, v127
	v_cvt_pk_f16_f32 v150, v116, v117
	v_cvt_pk_f16_f32 v151, v118, v119
	global_store_dwordx4 v146, v[148:151], s[86:87]
	v_pk_add_f32 v[120:121], v[120:121], v[136:137]
	v_pk_add_f32 v[122:123], v[122:123], v[138:139]
	v_pk_add_f32 v[112:113], v[112:113], v[140:141]
	v_pk_add_f32 v[114:115], v[114:115], v[142:143]
	v_pk_mul_f32 v[120:121], v[120:121], v[144:145] op_sel_hi:[1,0]
	v_pk_mul_f32 v[122:123], v[122:123], v[144:145] op_sel_hi:[1,0]
	v_pk_mul_f32 v[112:113], v[112:113], v[144:145] op_sel_hi:[1,0]
	v_pk_mul_f32 v[114:115], v[114:115], v[144:145] op_sel_hi:[1,0]
	v_exp_f32_e64 v120, v120
	v_exp_f32_e64 v121, v121
	v_exp_f32_e64 v122, v122
	v_exp_f32_e64 v123, v123
	v_exp_f32_e64 v112, v112
	v_exp_f32_e64 v113, v113
	v_exp_f32_e64 v114, v114
	v_exp_f32_e64 v115, v115
	v_pk_add_f32 v[120:121], v[120:121], 1.0 op_sel_hi:[1,0]
	v_pk_add_f32 v[122:123], v[122:123], 1.0 op_sel_hi:[1,0]
	v_pk_add_f32 v[112:113], v[112:113], 1.0 op_sel_hi:[1,0]
	v_pk_add_f32 v[114:115], v[114:115], 1.0 op_sel_hi:[1,0]
	v_rcp_f32_e64 v120, v120
	v_rcp_f32_e64 v121, v121
	v_rcp_f32_e64 v122, v122
	v_rcp_f32_e64 v123, v123
	v_rcp_f32_e64 v112, v112
	v_rcp_f32_e64 v113, v113
	v_rcp_f32_e64 v114, v114
	v_rcp_f32_e64 v115, v115
	v_pk_mul_f32 v[120:121], v[120:121], v[158:159] op_sel_hi:[1,0]
	v_pk_mul_f32 v[122:123], v[122:123], v[158:159] op_sel_hi:[1,0]
	v_pk_mul_f32 v[112:113], v[112:113], v[158:159] op_sel_hi:[1,0]
	v_pk_mul_f32 v[114:115], v[114:115], v[158:159] op_sel_hi:[1,0]
	v_cvt_pk_f16_f32 v152, v120, v121
	v_cvt_pk_f16_f32 v153, v122, v123
	v_cvt_pk_f16_f32 v154, v112, v113
	v_cvt_pk_f16_f32 v155, v114, v115
	global_store_dwordx4 v146, v[152:155], s[86:87] offset:256
	v_add_u32_e32 v146, 0x4000, v146
	v_pk_add_f32 v[108:109], v[108:109], v[128:129]
	v_pk_add_f32 v[110:111], v[110:111], v[130:131]
	v_pk_add_f32 v[100:101], v[100:101], v[132:133]
	v_pk_add_f32 v[102:103], v[102:103], v[134:135]
	v_pk_mul_f32 v[108:109], v[108:109], v[144:145] op_sel_hi:[1,0]
	v_pk_mul_f32 v[110:111], v[110:111], v[144:145] op_sel_hi:[1,0]
	v_pk_mul_f32 v[100:101], v[100:101], v[144:145] op_sel_hi:[1,0]
	v_pk_mul_f32 v[102:103], v[102:103], v[144:145] op_sel_hi:[1,0]
	v_exp_f32_e64 v108, v108
	v_exp_f32_e64 v109, v109
	v_exp_f32_e64 v110, v110
	v_exp_f32_e64 v111, v111
	v_exp_f32_e64 v100, v100
	v_exp_f32_e64 v101, v101
	v_exp_f32_e64 v102, v102
	v_exp_f32_e64 v103, v103
	v_pk_add_f32 v[108:109], v[108:109], 1.0 op_sel_hi:[1,0]
	v_pk_add_f32 v[110:111], v[110:111], 1.0 op_sel_hi:[1,0]
	v_pk_add_f32 v[100:101], v[100:101], 1.0 op_sel_hi:[1,0]
	v_pk_add_f32 v[102:103], v[102:103], 1.0 op_sel_hi:[1,0]
	v_rcp_f32_e64 v108, v108
	v_rcp_f32_e64 v109, v109
	v_rcp_f32_e64 v110, v110
	v_rcp_f32_e64 v111, v111
	v_rcp_f32_e64 v100, v100
	v_rcp_f32_e64 v101, v101
	v_rcp_f32_e64 v102, v102
	v_rcp_f32_e64 v103, v103
	v_pk_mul_f32 v[108:109], v[108:109], v[158:159] op_sel_hi:[1,0]
	v_pk_mul_f32 v[110:111], v[110:111], v[158:159] op_sel_hi:[1,0]
	v_pk_mul_f32 v[100:101], v[100:101], v[158:159] op_sel_hi:[1,0]
	v_pk_mul_f32 v[102:103], v[102:103], v[158:159] op_sel_hi:[1,0]
	v_cvt_pk_f16_f32 v148, v108, v109
	v_cvt_pk_f16_f32 v149, v110, v111
	v_cvt_pk_f16_f32 v150, v100, v101
	v_cvt_pk_f16_f32 v151, v102, v103
	global_store_dwordx4 v146, v[148:151], s[86:87]
	v_pk_add_f32 v[104:105], v[104:105], v[136:137]
	v_pk_add_f32 v[106:107], v[106:107], v[138:139]
	v_pk_add_f32 v[96:97], v[96:97], v[140:141]
	v_pk_add_f32 v[98:99], v[98:99], v[142:143]
	v_pk_mul_f32 v[104:105], v[104:105], v[144:145] op_sel_hi:[1,0]
	v_pk_mul_f32 v[106:107], v[106:107], v[144:145] op_sel_hi:[1,0]
	v_pk_mul_f32 v[96:97], v[96:97], v[144:145] op_sel_hi:[1,0]
	v_pk_mul_f32 v[98:99], v[98:99], v[144:145] op_sel_hi:[1,0]
	v_exp_f32_e64 v104, v104
	v_exp_f32_e64 v105, v105
	v_exp_f32_e64 v106, v106
	v_exp_f32_e64 v107, v107
	v_exp_f32_e64 v96, v96
	v_exp_f32_e64 v97, v97
	v_exp_f32_e64 v98, v98
	v_exp_f32_e64 v99, v99
	v_pk_add_f32 v[104:105], v[104:105], 1.0 op_sel_hi:[1,0]
	v_pk_add_f32 v[106:107], v[106:107], 1.0 op_sel_hi:[1,0]
	v_pk_add_f32 v[96:97], v[96:97], 1.0 op_sel_hi:[1,0]
	v_pk_add_f32 v[98:99], v[98:99], 1.0 op_sel_hi:[1,0]
	v_rcp_f32_e64 v104, v104
	v_rcp_f32_e64 v105, v105
	v_rcp_f32_e64 v106, v106
	v_rcp_f32_e64 v107, v107
	v_rcp_f32_e64 v96, v96
	v_rcp_f32_e64 v97, v97
	v_rcp_f32_e64 v98, v98
	v_rcp_f32_e64 v99, v99
	v_pk_mul_f32 v[104:105], v[104:105], v[158:159] op_sel_hi:[1,0]
	v_pk_mul_f32 v[106:107], v[106:107], v[158:159] op_sel_hi:[1,0]
	v_pk_mul_f32 v[96:97], v[96:97], v[158:159] op_sel_hi:[1,0]
	v_pk_mul_f32 v[98:99], v[98:99], v[158:159] op_sel_hi:[1,0]
	v_cvt_pk_f16_f32 v152, v104, v105
	v_cvt_pk_f16_f32 v153, v106, v107
	v_cvt_pk_f16_f32 v154, v96, v97
	v_cvt_pk_f16_f32 v155, v98, v99
	global_store_dwordx4 v146, v[152:155], s[86:87] offset:256
	v_add_u32_e32 v146, 0x4000, v146
	v_pk_add_f32 v[92:93], v[92:93], v[128:129]
	v_pk_add_f32 v[94:95], v[94:95], v[130:131]
	v_pk_add_f32 v[84:85], v[84:85], v[132:133]
	v_pk_add_f32 v[86:87], v[86:87], v[134:135]
	v_pk_mul_f32 v[92:93], v[92:93], v[144:145] op_sel_hi:[1,0]
	v_pk_mul_f32 v[94:95], v[94:95], v[144:145] op_sel_hi:[1,0]
	v_pk_mul_f32 v[84:85], v[84:85], v[144:145] op_sel_hi:[1,0]
	v_pk_mul_f32 v[86:87], v[86:87], v[144:145] op_sel_hi:[1,0]
	v_exp_f32_e64 v92, v92
	v_exp_f32_e64 v93, v93
	v_exp_f32_e64 v94, v94
	v_exp_f32_e64 v95, v95
	v_exp_f32_e64 v84, v84
	v_exp_f32_e64 v85, v85
	v_exp_f32_e64 v86, v86
	v_exp_f32_e64 v87, v87
	v_pk_add_f32 v[92:93], v[92:93], 1.0 op_sel_hi:[1,0]
	v_pk_add_f32 v[94:95], v[94:95], 1.0 op_sel_hi:[1,0]
	v_pk_add_f32 v[84:85], v[84:85], 1.0 op_sel_hi:[1,0]
	v_pk_add_f32 v[86:87], v[86:87], 1.0 op_sel_hi:[1,0]
	v_rcp_f32_e64 v92, v92
	v_rcp_f32_e64 v93, v93
	v_rcp_f32_e64 v94, v94
	v_rcp_f32_e64 v95, v95
	v_rcp_f32_e64 v84, v84
	v_rcp_f32_e64 v85, v85
	v_rcp_f32_e64 v86, v86
	v_rcp_f32_e64 v87, v87
	v_pk_mul_f32 v[92:93], v[92:93], v[158:159] op_sel_hi:[1,0]
	v_pk_mul_f32 v[94:95], v[94:95], v[158:159] op_sel_hi:[1,0]
	v_pk_mul_f32 v[84:85], v[84:85], v[158:159] op_sel_hi:[1,0]
	v_pk_mul_f32 v[86:87], v[86:87], v[158:159] op_sel_hi:[1,0]
	v_cvt_pk_f16_f32 v148, v92, v93
	v_cvt_pk_f16_f32 v149, v94, v95
	v_cvt_pk_f16_f32 v150, v84, v85
	v_cvt_pk_f16_f32 v151, v86, v87
	global_store_dwordx4 v146, v[148:151], s[86:87]
	v_pk_add_f32 v[88:89], v[88:89], v[136:137]
	v_pk_add_f32 v[90:91], v[90:91], v[138:139]
	v_pk_add_f32 v[80:81], v[80:81], v[140:141]
	v_pk_add_f32 v[82:83], v[82:83], v[142:143]
	v_pk_mul_f32 v[88:89], v[88:89], v[144:145] op_sel_hi:[1,0]
	v_pk_mul_f32 v[90:91], v[90:91], v[144:145] op_sel_hi:[1,0]
	v_pk_mul_f32 v[80:81], v[80:81], v[144:145] op_sel_hi:[1,0]
	v_pk_mul_f32 v[82:83], v[82:83], v[144:145] op_sel_hi:[1,0]
	v_exp_f32_e64 v88, v88
	v_exp_f32_e64 v89, v89
	v_exp_f32_e64 v90, v90
	v_exp_f32_e64 v91, v91
	v_exp_f32_e64 v80, v80
	v_exp_f32_e64 v81, v81
	v_exp_f32_e64 v82, v82
	v_exp_f32_e64 v83, v83
	v_pk_add_f32 v[88:89], v[88:89], 1.0 op_sel_hi:[1,0]
	v_pk_add_f32 v[90:91], v[90:91], 1.0 op_sel_hi:[1,0]
	v_pk_add_f32 v[80:81], v[80:81], 1.0 op_sel_hi:[1,0]
	v_pk_add_f32 v[82:83], v[82:83], 1.0 op_sel_hi:[1,0]
	v_rcp_f32_e64 v88, v88
	v_rcp_f32_e64 v89, v89
	v_rcp_f32_e64 v90, v90
	v_rcp_f32_e64 v91, v91
	v_rcp_f32_e64 v80, v80
	v_rcp_f32_e64 v81, v81
	v_rcp_f32_e64 v82, v82
	v_rcp_f32_e64 v83, v83
	v_pk_mul_f32 v[88:89], v[88:89], v[158:159] op_sel_hi:[1,0]
	v_pk_mul_f32 v[90:91], v[90:91], v[158:159] op_sel_hi:[1,0]
	v_pk_mul_f32 v[80:81], v[80:81], v[158:159] op_sel_hi:[1,0]
	v_pk_mul_f32 v[82:83], v[82:83], v[158:159] op_sel_hi:[1,0]
	v_cvt_pk_f16_f32 v152, v88, v89
	v_cvt_pk_f16_f32 v153, v90, v91
	v_cvt_pk_f16_f32 v154, v80, v81
	v_cvt_pk_f16_f32 v155, v82, v83
	global_store_dwordx4 v146, v[152:155], s[86:87] offset:256
	v_add_u32_e32 v146, 0x4000, v146
	v_pk_add_f32 v[76:77], v[76:77], v[128:129]
	v_pk_add_f32 v[78:79], v[78:79], v[130:131]
	v_pk_add_f32 v[68:69], v[68:69], v[132:133]
	v_pk_add_f32 v[70:71], v[70:71], v[134:135]
	v_pk_mul_f32 v[76:77], v[76:77], v[144:145] op_sel_hi:[1,0]
	v_pk_mul_f32 v[78:79], v[78:79], v[144:145] op_sel_hi:[1,0]
	v_pk_mul_f32 v[68:69], v[68:69], v[144:145] op_sel_hi:[1,0]
	v_pk_mul_f32 v[70:71], v[70:71], v[144:145] op_sel_hi:[1,0]
	v_exp_f32_e64 v76, v76
	v_exp_f32_e64 v77, v77
	v_exp_f32_e64 v78, v78
	v_exp_f32_e64 v79, v79
	v_exp_f32_e64 v68, v68
	v_exp_f32_e64 v69, v69
	v_exp_f32_e64 v70, v70
	v_exp_f32_e64 v71, v71
	v_pk_add_f32 v[76:77], v[76:77], 1.0 op_sel_hi:[1,0]
	v_pk_add_f32 v[78:79], v[78:79], 1.0 op_sel_hi:[1,0]
	v_pk_add_f32 v[68:69], v[68:69], 1.0 op_sel_hi:[1,0]
	v_pk_add_f32 v[70:71], v[70:71], 1.0 op_sel_hi:[1,0]
	v_rcp_f32_e64 v76, v76
	v_rcp_f32_e64 v77, v77
	v_rcp_f32_e64 v78, v78
	v_rcp_f32_e64 v79, v79
	v_rcp_f32_e64 v68, v68
	v_rcp_f32_e64 v69, v69
	v_rcp_f32_e64 v70, v70
	v_rcp_f32_e64 v71, v71
	v_pk_mul_f32 v[76:77], v[76:77], v[158:159] op_sel_hi:[1,0]
	v_pk_mul_f32 v[78:79], v[78:79], v[158:159] op_sel_hi:[1,0]
	v_pk_mul_f32 v[68:69], v[68:69], v[158:159] op_sel_hi:[1,0]
	v_pk_mul_f32 v[70:71], v[70:71], v[158:159] op_sel_hi:[1,0]
	v_cvt_pk_f16_f32 v148, v76, v77
	v_cvt_pk_f16_f32 v149, v78, v79
	v_cvt_pk_f16_f32 v150, v68, v69
	v_cvt_pk_f16_f32 v151, v70, v71
	global_store_dwordx4 v146, v[148:151], s[86:87]
	v_pk_add_f32 v[72:73], v[72:73], v[136:137]
	v_pk_add_f32 v[74:75], v[74:75], v[138:139]
	v_pk_add_f32 v[64:65], v[64:65], v[140:141]
	v_pk_add_f32 v[66:67], v[66:67], v[142:143]
	v_pk_mul_f32 v[72:73], v[72:73], v[144:145] op_sel_hi:[1,0]
	v_pk_mul_f32 v[74:75], v[74:75], v[144:145] op_sel_hi:[1,0]
	v_pk_mul_f32 v[64:65], v[64:65], v[144:145] op_sel_hi:[1,0]
	v_pk_mul_f32 v[66:67], v[66:67], v[144:145] op_sel_hi:[1,0]
	v_exp_f32_e64 v72, v72
	v_exp_f32_e64 v73, v73
	v_exp_f32_e64 v74, v74
	v_exp_f32_e64 v75, v75
	v_exp_f32_e64 v64, v64
	v_exp_f32_e64 v65, v65
	v_exp_f32_e64 v66, v66
	v_exp_f32_e64 v67, v67
	v_pk_add_f32 v[72:73], v[72:73], 1.0 op_sel_hi:[1,0]
	v_pk_add_f32 v[74:75], v[74:75], 1.0 op_sel_hi:[1,0]
	v_pk_add_f32 v[64:65], v[64:65], 1.0 op_sel_hi:[1,0]
	v_pk_add_f32 v[66:67], v[66:67], 1.0 op_sel_hi:[1,0]
	v_rcp_f32_e64 v72, v72
	v_rcp_f32_e64 v73, v73
	v_rcp_f32_e64 v74, v74
	v_rcp_f32_e64 v75, v75
	v_rcp_f32_e64 v64, v64
	v_rcp_f32_e64 v65, v65
	v_rcp_f32_e64 v66, v66
	v_rcp_f32_e64 v67, v67
	v_pk_mul_f32 v[72:73], v[72:73], v[158:159] op_sel_hi:[1,0]
	v_pk_mul_f32 v[74:75], v[74:75], v[158:159] op_sel_hi:[1,0]
	v_pk_mul_f32 v[64:65], v[64:65], v[158:159] op_sel_hi:[1,0]
	v_pk_mul_f32 v[66:67], v[66:67], v[158:159] op_sel_hi:[1,0]
	v_cvt_pk_f16_f32 v152, v72, v73
	v_cvt_pk_f16_f32 v153, v74, v75
	v_cvt_pk_f16_f32 v154, v64, v65
	v_cvt_pk_f16_f32 v155, v66, v67
	global_store_dwordx4 v146, v[152:155], s[86:87] offset:256
	v_add_u32_e32 v146, 0x14000, v146
	v_pk_add_f32 v[60:61], v[60:61], v[128:129]
	v_pk_add_f32 v[62:63], v[62:63], v[130:131]
	v_pk_add_f32 v[52:53], v[52:53], v[132:133]
	v_pk_add_f32 v[54:55], v[54:55], v[134:135]
	v_pk_mul_f32 v[60:61], v[60:61], v[144:145] op_sel_hi:[1,0]
	v_pk_mul_f32 v[62:63], v[62:63], v[144:145] op_sel_hi:[1,0]
	v_pk_mul_f32 v[52:53], v[52:53], v[144:145] op_sel_hi:[1,0]
	v_pk_mul_f32 v[54:55], v[54:55], v[144:145] op_sel_hi:[1,0]
	v_exp_f32_e64 v60, v60
	v_exp_f32_e64 v61, v61
	v_exp_f32_e64 v62, v62
	v_exp_f32_e64 v63, v63
	v_exp_f32_e64 v52, v52
	v_exp_f32_e64 v53, v53
	v_exp_f32_e64 v54, v54
	v_exp_f32_e64 v55, v55
	v_pk_add_f32 v[60:61], v[60:61], 1.0 op_sel_hi:[1,0]
	v_pk_add_f32 v[62:63], v[62:63], 1.0 op_sel_hi:[1,0]
	v_pk_add_f32 v[52:53], v[52:53], 1.0 op_sel_hi:[1,0]
	v_pk_add_f32 v[54:55], v[54:55], 1.0 op_sel_hi:[1,0]
	v_rcp_f32_e64 v60, v60
	v_rcp_f32_e64 v61, v61
	v_rcp_f32_e64 v62, v62
	v_rcp_f32_e64 v63, v63
	v_rcp_f32_e64 v52, v52
	v_rcp_f32_e64 v53, v53
	v_rcp_f32_e64 v54, v54
	v_rcp_f32_e64 v55, v55
	v_pk_mul_f32 v[60:61], v[60:61], v[158:159] op_sel_hi:[1,0]
	v_pk_mul_f32 v[62:63], v[62:63], v[158:159] op_sel_hi:[1,0]
	v_pk_mul_f32 v[52:53], v[52:53], v[158:159] op_sel_hi:[1,0]
	v_pk_mul_f32 v[54:55], v[54:55], v[158:159] op_sel_hi:[1,0]
	v_cvt_pk_f16_f32 v148, v60, v61
	v_cvt_pk_f16_f32 v149, v62, v63
	v_cvt_pk_f16_f32 v150, v52, v53
	v_cvt_pk_f16_f32 v151, v54, v55
	global_store_dwordx4 v146, v[148:151], s[86:87]
	v_pk_add_f32 v[56:57], v[56:57], v[136:137]
	v_pk_add_f32 v[58:59], v[58:59], v[138:139]
	v_pk_add_f32 v[48:49], v[48:49], v[140:141]
	v_pk_add_f32 v[50:51], v[50:51], v[142:143]
	v_pk_mul_f32 v[56:57], v[56:57], v[144:145] op_sel_hi:[1,0]
	v_pk_mul_f32 v[58:59], v[58:59], v[144:145] op_sel_hi:[1,0]
	v_pk_mul_f32 v[48:49], v[48:49], v[144:145] op_sel_hi:[1,0]
	v_pk_mul_f32 v[50:51], v[50:51], v[144:145] op_sel_hi:[1,0]
	v_exp_f32_e64 v56, v56
	v_exp_f32_e64 v57, v57
	v_exp_f32_e64 v58, v58
	v_exp_f32_e64 v59, v59
	v_exp_f32_e64 v48, v48
	v_exp_f32_e64 v49, v49
	v_exp_f32_e64 v50, v50
	v_exp_f32_e64 v51, v51
	v_pk_add_f32 v[56:57], v[56:57], 1.0 op_sel_hi:[1,0]
	v_pk_add_f32 v[58:59], v[58:59], 1.0 op_sel_hi:[1,0]
	v_pk_add_f32 v[48:49], v[48:49], 1.0 op_sel_hi:[1,0]
	v_pk_add_f32 v[50:51], v[50:51], 1.0 op_sel_hi:[1,0]
	v_rcp_f32_e64 v56, v56
	v_rcp_f32_e64 v57, v57
	v_rcp_f32_e64 v58, v58
	v_rcp_f32_e64 v59, v59
	v_rcp_f32_e64 v48, v48
	v_rcp_f32_e64 v49, v49
	v_rcp_f32_e64 v50, v50
	v_rcp_f32_e64 v51, v51
	v_pk_mul_f32 v[56:57], v[56:57], v[158:159] op_sel_hi:[1,0]
	v_pk_mul_f32 v[58:59], v[58:59], v[158:159] op_sel_hi:[1,0]
	v_pk_mul_f32 v[48:49], v[48:49], v[158:159] op_sel_hi:[1,0]
	v_pk_mul_f32 v[50:51], v[50:51], v[158:159] op_sel_hi:[1,0]
	v_cvt_pk_f16_f32 v152, v56, v57
	v_cvt_pk_f16_f32 v153, v58, v59
	v_cvt_pk_f16_f32 v154, v48, v49
	v_cvt_pk_f16_f32 v155, v50, v51
	global_store_dwordx4 v146, v[152:155], s[86:87] offset:256
	v_add_u32_e32 v146, 0x4000, v146
	v_pk_add_f32 v[44:45], v[44:45], v[128:129]
	v_pk_add_f32 v[46:47], v[46:47], v[130:131]
	v_pk_add_f32 v[36:37], v[36:37], v[132:133]
	v_pk_add_f32 v[38:39], v[38:39], v[134:135]
	v_pk_mul_f32 v[44:45], v[44:45], v[144:145] op_sel_hi:[1,0]
	v_pk_mul_f32 v[46:47], v[46:47], v[144:145] op_sel_hi:[1,0]
	v_pk_mul_f32 v[36:37], v[36:37], v[144:145] op_sel_hi:[1,0]
	v_pk_mul_f32 v[38:39], v[38:39], v[144:145] op_sel_hi:[1,0]
	v_exp_f32_e64 v44, v44
	v_exp_f32_e64 v45, v45
	v_exp_f32_e64 v46, v46
	v_exp_f32_e64 v47, v47
	v_exp_f32_e64 v36, v36
	v_exp_f32_e64 v37, v37
	v_exp_f32_e64 v38, v38
	v_exp_f32_e64 v39, v39
	v_pk_add_f32 v[44:45], v[44:45], 1.0 op_sel_hi:[1,0]
	v_pk_add_f32 v[46:47], v[46:47], 1.0 op_sel_hi:[1,0]
	v_pk_add_f32 v[36:37], v[36:37], 1.0 op_sel_hi:[1,0]
	v_pk_add_f32 v[38:39], v[38:39], 1.0 op_sel_hi:[1,0]
	v_rcp_f32_e64 v44, v44
	v_rcp_f32_e64 v45, v45
	v_rcp_f32_e64 v46, v46
	v_rcp_f32_e64 v47, v47
	v_rcp_f32_e64 v36, v36
	v_rcp_f32_e64 v37, v37
	v_rcp_f32_e64 v38, v38
	v_rcp_f32_e64 v39, v39
	v_pk_mul_f32 v[44:45], v[44:45], v[158:159] op_sel_hi:[1,0]
	v_pk_mul_f32 v[46:47], v[46:47], v[158:159] op_sel_hi:[1,0]
	v_pk_mul_f32 v[36:37], v[36:37], v[158:159] op_sel_hi:[1,0]
	v_pk_mul_f32 v[38:39], v[38:39], v[158:159] op_sel_hi:[1,0]
	v_cvt_pk_f16_f32 v148, v44, v45
	v_cvt_pk_f16_f32 v149, v46, v47
	v_cvt_pk_f16_f32 v150, v36, v37
	v_cvt_pk_f16_f32 v151, v38, v39
	global_store_dwordx4 v146, v[148:151], s[86:87]
	v_pk_add_f32 v[40:41], v[40:41], v[136:137]
	v_pk_add_f32 v[42:43], v[42:43], v[138:139]
	v_pk_add_f32 v[32:33], v[32:33], v[140:141]
	v_pk_add_f32 v[34:35], v[34:35], v[142:143]
	v_pk_mul_f32 v[40:41], v[40:41], v[144:145] op_sel_hi:[1,0]
	v_pk_mul_f32 v[42:43], v[42:43], v[144:145] op_sel_hi:[1,0]
	v_pk_mul_f32 v[32:33], v[32:33], v[144:145] op_sel_hi:[1,0]
	v_pk_mul_f32 v[34:35], v[34:35], v[144:145] op_sel_hi:[1,0]
	v_exp_f32_e64 v40, v40
	v_exp_f32_e64 v41, v41
	v_exp_f32_e64 v42, v42
	v_exp_f32_e64 v43, v43
	v_exp_f32_e64 v32, v32
	v_exp_f32_e64 v33, v33
	v_exp_f32_e64 v34, v34
	v_exp_f32_e64 v35, v35
	v_pk_add_f32 v[40:41], v[40:41], 1.0 op_sel_hi:[1,0]
	v_pk_add_f32 v[42:43], v[42:43], 1.0 op_sel_hi:[1,0]
	v_pk_add_f32 v[32:33], v[32:33], 1.0 op_sel_hi:[1,0]
	v_pk_add_f32 v[34:35], v[34:35], 1.0 op_sel_hi:[1,0]
	v_rcp_f32_e64 v40, v40
	v_rcp_f32_e64 v41, v41
	v_rcp_f32_e64 v42, v42
	v_rcp_f32_e64 v43, v43
	v_rcp_f32_e64 v32, v32
	v_rcp_f32_e64 v33, v33
	v_rcp_f32_e64 v34, v34
	v_rcp_f32_e64 v35, v35
	v_pk_mul_f32 v[40:41], v[40:41], v[158:159] op_sel_hi:[1,0]
	v_pk_mul_f32 v[42:43], v[42:43], v[158:159] op_sel_hi:[1,0]
	v_pk_mul_f32 v[32:33], v[32:33], v[158:159] op_sel_hi:[1,0]
	v_pk_mul_f32 v[34:35], v[34:35], v[158:159] op_sel_hi:[1,0]
	v_cvt_pk_f16_f32 v152, v40, v41
	v_cvt_pk_f16_f32 v153, v42, v43
	v_cvt_pk_f16_f32 v154, v32, v33
	v_cvt_pk_f16_f32 v155, v34, v35
	global_store_dwordx4 v146, v[152:155], s[86:87] offset:256
	v_add_u32_e32 v146, 0x4000, v146
	v_pk_add_f32 v[28:29], v[28:29], v[128:129]
	v_pk_add_f32 v[30:31], v[30:31], v[130:131]
	v_pk_add_f32 v[20:21], v[20:21], v[132:133]
	v_pk_add_f32 v[22:23], v[22:23], v[134:135]
	v_pk_mul_f32 v[28:29], v[28:29], v[144:145] op_sel_hi:[1,0]
	v_pk_mul_f32 v[30:31], v[30:31], v[144:145] op_sel_hi:[1,0]
	v_pk_mul_f32 v[20:21], v[20:21], v[144:145] op_sel_hi:[1,0]
	v_pk_mul_f32 v[22:23], v[22:23], v[144:145] op_sel_hi:[1,0]
	v_exp_f32_e64 v28, v28
	v_exp_f32_e64 v29, v29
	v_exp_f32_e64 v30, v30
	v_exp_f32_e64 v31, v31
	v_exp_f32_e64 v20, v20
	v_exp_f32_e64 v21, v21
	v_exp_f32_e64 v22, v22
	v_exp_f32_e64 v23, v23
	v_pk_add_f32 v[28:29], v[28:29], 1.0 op_sel_hi:[1,0]
	v_pk_add_f32 v[30:31], v[30:31], 1.0 op_sel_hi:[1,0]
	v_pk_add_f32 v[20:21], v[20:21], 1.0 op_sel_hi:[1,0]
	v_pk_add_f32 v[22:23], v[22:23], 1.0 op_sel_hi:[1,0]
	v_rcp_f32_e64 v28, v28
	v_rcp_f32_e64 v29, v29
	v_rcp_f32_e64 v30, v30
	v_rcp_f32_e64 v31, v31
	v_rcp_f32_e64 v20, v20
	v_rcp_f32_e64 v21, v21
	v_rcp_f32_e64 v22, v22
	v_rcp_f32_e64 v23, v23
	v_pk_mul_f32 v[28:29], v[28:29], v[158:159] op_sel_hi:[1,0]
	v_pk_mul_f32 v[30:31], v[30:31], v[158:159] op_sel_hi:[1,0]
	v_pk_mul_f32 v[20:21], v[20:21], v[158:159] op_sel_hi:[1,0]
	v_pk_mul_f32 v[22:23], v[22:23], v[158:159] op_sel_hi:[1,0]
	v_cvt_pk_f16_f32 v148, v28, v29
	v_cvt_pk_f16_f32 v149, v30, v31
	v_cvt_pk_f16_f32 v150, v20, v21
	v_cvt_pk_f16_f32 v151, v22, v23
	global_store_dwordx4 v146, v[148:151], s[86:87]
	v_pk_add_f32 v[24:25], v[24:25], v[136:137]
	v_pk_add_f32 v[26:27], v[26:27], v[138:139]
	v_pk_add_f32 v[16:17], v[16:17], v[140:141]
	v_pk_add_f32 v[18:19], v[18:19], v[142:143]
	v_pk_mul_f32 v[24:25], v[24:25], v[144:145] op_sel_hi:[1,0]
	v_pk_mul_f32 v[26:27], v[26:27], v[144:145] op_sel_hi:[1,0]
	v_pk_mul_f32 v[16:17], v[16:17], v[144:145] op_sel_hi:[1,0]
	v_pk_mul_f32 v[18:19], v[18:19], v[144:145] op_sel_hi:[1,0]
	v_exp_f32_e64 v24, v24
	v_exp_f32_e64 v25, v25
	v_exp_f32_e64 v26, v26
	v_exp_f32_e64 v27, v27
	v_exp_f32_e64 v16, v16
	v_exp_f32_e64 v17, v17
	v_exp_f32_e64 v18, v18
	v_exp_f32_e64 v19, v19
	v_pk_add_f32 v[24:25], v[24:25], 1.0 op_sel_hi:[1,0]
	v_pk_add_f32 v[26:27], v[26:27], 1.0 op_sel_hi:[1,0]
	v_pk_add_f32 v[16:17], v[16:17], 1.0 op_sel_hi:[1,0]
	v_pk_add_f32 v[18:19], v[18:19], 1.0 op_sel_hi:[1,0]
	v_rcp_f32_e64 v24, v24
	v_rcp_f32_e64 v25, v25
	v_rcp_f32_e64 v26, v26
	v_rcp_f32_e64 v27, v27
	v_rcp_f32_e64 v16, v16
	v_rcp_f32_e64 v17, v17
	v_rcp_f32_e64 v18, v18
	v_rcp_f32_e64 v19, v19
	v_pk_mul_f32 v[24:25], v[24:25], v[158:159] op_sel_hi:[1,0]
	v_pk_mul_f32 v[26:27], v[26:27], v[158:159] op_sel_hi:[1,0]
	v_pk_mul_f32 v[16:17], v[16:17], v[158:159] op_sel_hi:[1,0]
	v_pk_mul_f32 v[18:19], v[18:19], v[158:159] op_sel_hi:[1,0]
	v_cvt_pk_f16_f32 v152, v24, v25
	v_cvt_pk_f16_f32 v153, v26, v27
	v_cvt_pk_f16_f32 v154, v16, v17
	v_cvt_pk_f16_f32 v155, v18, v19
	global_store_dwordx4 v146, v[152:155], s[86:87] offset:256
	v_add_u32_e32 v146, 0x4000, v146
	v_pk_add_f32 v[12:13], v[12:13], v[128:129]
	v_pk_add_f32 v[14:15], v[14:15], v[130:131]
	v_pk_add_f32 v[4:5], v[4:5], v[132:133]
	v_pk_add_f32 v[6:7], v[6:7], v[134:135]
	v_pk_mul_f32 v[12:13], v[12:13], v[144:145] op_sel_hi:[1,0]
	v_pk_mul_f32 v[14:15], v[14:15], v[144:145] op_sel_hi:[1,0]
	v_pk_mul_f32 v[4:5], v[4:5], v[144:145] op_sel_hi:[1,0]
	v_pk_mul_f32 v[6:7], v[6:7], v[144:145] op_sel_hi:[1,0]
	v_exp_f32_e64 v12, v12
	v_exp_f32_e64 v13, v13
	v_exp_f32_e64 v14, v14
	v_exp_f32_e64 v15, v15
	v_exp_f32_e64 v4, v4
	v_exp_f32_e64 v5, v5
	v_exp_f32_e64 v6, v6
	v_exp_f32_e64 v7, v7
	v_pk_add_f32 v[12:13], v[12:13], 1.0 op_sel_hi:[1,0]
	v_pk_add_f32 v[14:15], v[14:15], 1.0 op_sel_hi:[1,0]
	v_pk_add_f32 v[4:5], v[4:5], 1.0 op_sel_hi:[1,0]
	v_pk_add_f32 v[6:7], v[6:7], 1.0 op_sel_hi:[1,0]
	v_rcp_f32_e64 v12, v12
	v_rcp_f32_e64 v13, v13
	v_rcp_f32_e64 v14, v14
	v_rcp_f32_e64 v15, v15
	v_rcp_f32_e64 v4, v4
	v_rcp_f32_e64 v5, v5
	v_rcp_f32_e64 v6, v6
	v_rcp_f32_e64 v7, v7
	v_pk_mul_f32 v[12:13], v[12:13], v[158:159] op_sel_hi:[1,0]
	v_pk_mul_f32 v[14:15], v[14:15], v[158:159] op_sel_hi:[1,0]
	v_pk_mul_f32 v[4:5], v[4:5], v[158:159] op_sel_hi:[1,0]
	v_pk_mul_f32 v[6:7], v[6:7], v[158:159] op_sel_hi:[1,0]
	v_cvt_pk_f16_f32 v148, v12, v13
	v_cvt_pk_f16_f32 v149, v14, v15
	v_cvt_pk_f16_f32 v150, v4, v5
	v_cvt_pk_f16_f32 v151, v6, v7
	global_store_dwordx4 v146, v[148:151], s[86:87]
	v_pk_add_f32 v[8:9], v[8:9], v[136:137]
	v_pk_add_f32 v[10:11], v[10:11], v[138:139]
	v_pk_add_f32 v[0:1], v[0:1], v[140:141]
	v_pk_add_f32 v[2:3], v[2:3], v[142:143]
	v_pk_mul_f32 v[8:9], v[8:9], v[144:145] op_sel_hi:[1,0]
	v_pk_mul_f32 v[10:11], v[10:11], v[144:145] op_sel_hi:[1,0]
	v_pk_mul_f32 v[0:1], v[0:1], v[144:145] op_sel_hi:[1,0]
	v_pk_mul_f32 v[2:3], v[2:3], v[144:145] op_sel_hi:[1,0]
	v_exp_f32_e64 v8, v8
	v_exp_f32_e64 v9, v9
	v_exp_f32_e64 v10, v10
	v_exp_f32_e64 v11, v11
	v_exp_f32_e64 v0, v0
	v_exp_f32_e64 v1, v1
	v_exp_f32_e64 v2, v2
	v_exp_f32_e64 v3, v3
	v_pk_add_f32 v[8:9], v[8:9], 1.0 op_sel_hi:[1,0]
	v_pk_add_f32 v[10:11], v[10:11], 1.0 op_sel_hi:[1,0]
	v_pk_add_f32 v[0:1], v[0:1], 1.0 op_sel_hi:[1,0]
	v_pk_add_f32 v[2:3], v[2:3], 1.0 op_sel_hi:[1,0]
	v_rcp_f32_e64 v8, v8
	v_rcp_f32_e64 v9, v9
	v_rcp_f32_e64 v10, v10
	v_rcp_f32_e64 v11, v11
	v_rcp_f32_e64 v0, v0
	v_rcp_f32_e64 v1, v1
	v_rcp_f32_e64 v2, v2
	v_rcp_f32_e64 v3, v3
	v_pk_mul_f32 v[8:9], v[8:9], v[158:159] op_sel_hi:[1,0]
	v_pk_mul_f32 v[10:11], v[10:11], v[158:159] op_sel_hi:[1,0]
	v_pk_mul_f32 v[0:1], v[0:1], v[158:159] op_sel_hi:[1,0]
	v_pk_mul_f32 v[2:3], v[2:3], v[158:159] op_sel_hi:[1,0]
	v_cvt_pk_f16_f32 v152, v8, v9
	v_cvt_pk_f16_f32 v153, v10, v11
	v_cvt_pk_f16_f32 v154, v0, v1
	v_cvt_pk_f16_f32 v155, v2, v3
	global_store_dwordx4 v146, v[152:155], s[86:87] offset:256
	s_branch .Lepi3_done
.Lepi3_plain:
	s_nop 0
	v_cvt_pk_bf16_f32 v148, v124, v125
	v_cvt_pk_bf16_f32 v149, v126, v127
	v_cvt_pk_bf16_f32 v150, v116, v117
	v_cvt_pk_bf16_f32 v151, v118, v119
	global_store_dwordx4 v146, v[148:151], s[86:87]
	v_cvt_pk_bf16_f32 v152, v120, v121
	v_cvt_pk_bf16_f32 v153, v122, v123
	v_cvt_pk_bf16_f32 v154, v112, v113
	v_cvt_pk_bf16_f32 v155, v114, v115
	global_store_dwordx4 v146, v[152:155], s[86:87] offset:256
	v_add_u32_e32 v146, 0x4000, v146
	v_cvt_pk_bf16_f32 v148, v108, v109
	v_cvt_pk_bf16_f32 v149, v110, v111
	v_cvt_pk_bf16_f32 v150, v100, v101
	v_cvt_pk_bf16_f32 v151, v102, v103
	global_store_dwordx4 v146, v[148:151], s[86:87]
	v_cvt_pk_bf16_f32 v152, v104, v105
	v_cvt_pk_bf16_f32 v153, v106, v107
	v_cvt_pk_bf16_f32 v154, v96, v97
	v_cvt_pk_bf16_f32 v155, v98, v99
	global_store_dwordx4 v146, v[152:155], s[86:87] offset:256
	v_add_u32_e32 v146, 0x4000, v146
	v_cvt_pk_bf16_f32 v148, v92, v93
	v_cvt_pk_bf16_f32 v149, v94, v95
	v_cvt_pk_bf16_f32 v150, v84, v85
	v_cvt_pk_bf16_f32 v151, v86, v87
	global_store_dwordx4 v146, v[148:151], s[86:87]
	v_cvt_pk_bf16_f32 v152, v88, v89
	v_cvt_pk_bf16_f32 v153, v90, v91
	v_cvt_pk_bf16_f32 v154, v80, v81
	v_cvt_pk_bf16_f32 v155, v82, v83
	global_store_dwordx4 v146, v[152:155], s[86:87] offset:256
	v_add_u32_e32 v146, 0x4000, v146
	v_cvt_pk_bf16_f32 v148, v76, v77
	v_cvt_pk_bf16_f32 v149, v78, v79
	v_cvt_pk_bf16_f32 v150, v68, v69
	v_cvt_pk_bf16_f32 v151, v70, v71
	global_store_dwordx4 v146, v[148:151], s[86:87]
	v_cvt_pk_bf16_f32 v152, v72, v73
	v_cvt_pk_bf16_f32 v153, v74, v75
	v_cvt_pk_bf16_f32 v154, v64, v65
	v_cvt_pk_bf16_f32 v155, v66, v67
	global_store_dwordx4 v146, v[152:155], s[86:87] offset:256
	v_add_u32_e32 v146, 0x14000, v146
	v_cvt_pk_bf16_f32 v148, v60, v61
	v_cvt_pk_bf16_f32 v149, v62, v63
	v_cvt_pk_bf16_f32 v150, v52, v53
	v_cvt_pk_bf16_f32 v151, v54, v55
	global_store_dwordx4 v146, v[148:151], s[86:87]
	v_cvt_pk_bf16_f32 v152, v56, v57
	v_cvt_pk_bf16_f32 v153, v58, v59
	v_cvt_pk_bf16_f32 v154, v48, v49
	v_cvt_pk_bf16_f32 v155, v50, v51
	global_store_dwordx4 v146, v[152:155], s[86:87] offset:256
	v_add_u32_e32 v146, 0x4000, v146
	v_cvt_pk_bf16_f32 v148, v44, v45
	v_cvt_pk_bf16_f32 v149, v46, v47
	v_cvt_pk_bf16_f32 v150, v36, v37
	v_cvt_pk_bf16_f32 v151, v38, v39
	global_store_dwordx4 v146, v[148:151], s[86:87]
	v_cvt_pk_bf16_f32 v152, v40, v41
	v_cvt_pk_bf16_f32 v153, v42, v43
	v_cvt_pk_bf16_f32 v154, v32, v33
	v_cvt_pk_bf16_f32 v155, v34, v35
	global_store_dwordx4 v146, v[152:155], s[86:87] offset:256
	v_add_u32_e32 v146, 0x4000, v146
	v_cvt_pk_bf16_f32 v148, v28, v29
	v_cvt_pk_bf16_f32 v149, v30, v31
	v_cvt_pk_bf16_f32 v150, v20, v21
	v_cvt_pk_bf16_f32 v151, v22, v23
	global_store_dwordx4 v146, v[148:151], s[86:87]
	v_cvt_pk_bf16_f32 v152, v24, v25
	v_cvt_pk_bf16_f32 v153, v26, v27
	v_cvt_pk_bf16_f32 v154, v16, v17
	v_cvt_pk_bf16_f32 v155, v18, v19
	global_store_dwordx4 v146, v[152:155], s[86:87] offset:256
	v_add_u32_e32 v146, 0x4000, v146
	v_cvt_pk_bf16_f32 v148, v12, v13
	v_cvt_pk_bf16_f32 v149, v14, v15
	v_cvt_pk_bf16_f32 v150, v4, v5
	v_cvt_pk_bf16_f32 v151, v6, v7
	global_store_dwordx4 v146, v[148:151], s[86:87]
	v_cvt_pk_bf16_f32 v152, v8, v9
	v_cvt_pk_bf16_f32 v153, v10, v11
	v_cvt_pk_bf16_f32 v154, v0, v1
	v_cvt_pk_bf16_f32 v155, v2, v3
	global_store_dwordx4 v146, v[152:155], s[86:87] offset:256

.LBB0_220:
	s_and_b64 vcc, exec, s[0:1]
	s_cbranch_vccz .LBB0_222
	s_nop 0
	v_lshl_or_b32 v128, s18, 8, v238
	s_ashr_i32 s0, s19, 5
	s_nop 0
	v_lshlrev_b32_e64 v176, 2, v128
	s_mul_i32 s0, s0, 0x9000
	s_add_u32 s0, s42, s0
	s_addc_u32 s1, s43, 0
	v_lshl_add_u32 v214, v196, 12, v176
	global_load_dwordx4 v[198:201], v176, s[0:1]
	global_load_dwordx4 v[202:205], v176, s[0:1] offset:16
	global_load_dwordx4 v[206:209], v176, s[0:1] offset:512
	global_load_dwordx4 v[210:213], v176, s[0:1] offset:528
	global_load_dwordx4 v[128:131], v214, s[92:93]
	global_load_dwordx4 v[132:135], v214, s[92:93] offset:16
	global_load_dwordx4 v[136:139], v214, s[92:93] offset:512
	global_load_dwordx4 v[140:143], v214, s[92:93] offset:528
	v_add_u32_e32 v215, 0x10000, v214
	global_load_dwordx4 v[144:147], v215, s[92:93]
	global_load_dwordx4 v[148:151], v215, s[92:93] offset:16
	global_load_dwordx4 v[152:155], v215, s[92:93] offset:512
	global_load_dwordx4 v[156:159], v215, s[92:93] offset:528
	v_add_u32_e32 v216, 0x20000, v214
	global_load_dwordx4 v[160:163], v216, s[92:93]
	global_load_dwordx4 v[164:167], v216, s[92:93] offset:16
	global_load_dwordx4 v[168:171], v216, s[92:93] offset:512
	global_load_dwordx4 v[172:175], v216, s[92:93] offset:528
	v_add_u32_e32 v217, 0x30000, v214
	v_add_u32_e32 v218, 0x80000, v214
	v_add_u32_e32 v219, 0x90000, v214
	v_add_u32_e32 v220, 0xa0000, v214
	v_add_u32_e32 v221, 0xb0000, v214
	s_waitcnt vmcnt(8)
	s_nop 0
	v_pk_mul_f32 v[198:199], v[198:199], s[94:95]
	v_pk_mul_f32 v[200:201], v[200:201], s[94:95]
	v_pk_mul_f32 v[202:203], v[202:203], s[94:95]
	v_pk_mul_f32 v[204:205], v[204:205], s[94:95]
	v_pk_mul_f32 v[206:207], v[206:207], s[94:95]
	v_pk_mul_f32 v[208:209], v[208:209], s[94:95]
	v_pk_mul_f32 v[210:211], v[210:211], s[94:95]
	v_pk_mul_f32 v[212:213], v[212:213], s[94:95]
	v_pk_fma_f32 v[128:129], v[124:125], v[198:199], v[128:129]
	v_pk_fma_f32 v[130:131], v[126:127], v[200:201], v[130:131]
	v_pk_fma_f32 v[132:133], v[116:117], v[202:203], v[132:133]
	v_pk_fma_f32 v[134:135], v[118:119], v[204:205], v[134:135]
	v_pk_fma_f32 v[136:137], v[120:121], v[206:207], v[136:137]
	v_pk_fma_f32 v[138:139], v[122:123], v[208:209], v[138:139]
	v_pk_fma_f32 v[140:141], v[112:113], v[210:211], v[140:141]
	v_pk_fma_f32 v[142:143], v[114:115], v[212:213], v[142:143]
	global_store_dwordx4 v214, v[128:131], s[90:91]
	global_store_dwordx4 v214, v[132:135], s[90:91] offset:16
	global_store_dwordx4 v214, v[136:139], s[90:91] offset:512
	global_store_dwordx4 v214, v[140:143], s[90:91] offset:528
	global_load_dwordx4 v[112:115], v217, s[92:93]
	global_load_dwordx4 v[116:119], v217, s[92:93] offset:16
	global_load_dwordx4 v[120:123], v217, s[92:93] offset:512
	global_load_dwordx4 v[124:127], v217, s[92:93] offset:528
	s_waitcnt vmcnt(12)
	s_nop 0
	v_pk_fma_f32 v[144:145], v[108:109], v[198:199], v[144:145]
	v_pk_fma_f32 v[146:147], v[110:111], v[200:201], v[146:147]
	v_pk_fma_f32 v[148:149], v[100:101], v[202:203], v[148:149]
	v_pk_fma_f32 v[150:151], v[102:103], v[204:205], v[150:151]
	v_pk_fma_f32 v[152:153], v[104:105], v[206:207], v[152:153]
	v_pk_fma_f32 v[154:155], v[106:107], v[208:209], v[154:155]
	v_pk_fma_f32 v[156:157], v[96:97], v[210:211], v[156:157]
	v_pk_fma_f32 v[158:159], v[98:99], v[212:213], v[158:159]
	global_store_dwordx4 v215, v[144:147], s[90:91]
	global_store_dwordx4 v215, v[148:151], s[90:91] offset:16
	global_store_dwordx4 v215, v[152:155], s[90:91] offset:512
	global_store_dwordx4 v215, v[156:159], s[90:91] offset:528
	global_load_dwordx4 v[96:99], v218, s[92:93]
	global_load_dwordx4 v[100:103], v218, s[92:93] offset:16
	global_load_dwordx4 v[104:107], v218, s[92:93] offset:512
	global_load_dwordx4 v[108:111], v218, s[92:93] offset:528
	s_waitcnt vmcnt(16)
	s_nop 0
	v_pk_fma_f32 v[160:161], v[92:93], v[198:199], v[160:161]
	v_pk_fma_f32 v[162:163], v[94:95], v[200:201], v[162:163]
	v_pk_fma_f32 v[164:165], v[84:85], v[202:203], v[164:165]
	v_pk_fma_f32 v[166:167], v[86:87], v[204:205], v[166:167]
	v_pk_fma_f32 v[168:169], v[88:89], v[206:207], v[168:169]
	v_pk_fma_f32 v[170:171], v[90:91], v[208:209], v[170:171]
	v_pk_fma_f32 v[172:173], v[80:81], v[210:211], v[172:173]
	v_pk_fma_f32 v[174:175], v[82:83], v[212:213], v[174:175]
	global_store_dwordx4 v216, v[160:163], s[90:91]
	global_store_dwordx4 v216, v[164:167], s[90:91] offset:16
	global_store_dwordx4 v216, v[168:171], s[90:91] offset:512
	global_store_dwordx4 v216, v[172:175], s[90:91] offset:528
	global_load_dwordx4 v[80:83], v219, s[92:93]
	global_load_dwordx4 v[84:87], v219, s[92:93] offset:16
	global_load_dwordx4 v[88:91], v219, s[92:93] offset:512
	global_load_dwordx4 v[92:95], v219, s[92:93] offset:528
	s_waitcnt vmcnt(16)
	s_nop 0
	v_pk_fma_f32 v[112:113], v[76:77], v[198:199], v[112:113]
	v_pk_fma_f32 v[114:115], v[78:79], v[200:201], v[114:115]
	v_pk_fma_f32 v[116:117], v[68:69], v[202:203], v[116:117]
	v_pk_fma_f32 v[118:119], v[70:71], v[204:205], v[118:119]
	v_pk_fma_f32 v[120:121], v[72:73], v[206:207], v[120:121]
	v_pk_fma_f32 v[122:123], v[74:75], v[208:209], v[122:123]
	v_pk_fma_f32 v[124:125], v[64:65], v[210:211], v[124:125]
	v_pk_fma_f32 v[126:127], v[66:67], v[212:213], v[126:127]
	global_store_dwordx4 v217, v[112:115], s[90:91]
	global_store_dwordx4 v217, v[116:119], s[90:91] offset:16
	global_store_dwordx4 v217, v[120:123], s[90:91] offset:512
	global_store_dwordx4 v217, v[124:127], s[90:91] offset:528
	global_load_dwordx4 v[64:67], v220, s[92:93]
	global_load_dwordx4 v[68:71], v220, s[92:93] offset:16
	global_load_dwordx4 v[72:75], v220, s[92:93] offset:512
	global_load_dwordx4 v[76:79], v220, s[92:93] offset:528
	s_waitcnt vmcnt(16)
	s_nop 0
	v_pk_fma_f32 v[96:97], v[60:61], v[198:199], v[96:97]
	v_pk_fma_f32 v[98:99], v[62:63], v[200:201], v[98:99]
	v_pk_fma_f32 v[100:101], v[52:53], v[202:203], v[100:101]
	v_pk_fma_f32 v[102:103], v[54:55], v[204:205], v[102:103]
	v_pk_fma_f32 v[104:105], v[56:57], v[206:207], v[104:105]
	v_pk_fma_f32 v[106:107], v[58:59], v[208:209], v[106:107]
	v_pk_fma_f32 v[108:109], v[48:49], v[210:211], v[108:109]
	v_pk_fma_f32 v[110:111], v[50:51], v[212:213], v[110:111]
	global_store_dwordx4 v218, v[96:99], s[90:91]
	global_store_dwordx4 v218, v[100:103], s[90:91] offset:16
	global_store_dwordx4 v218, v[104:107], s[90:91] offset:512
	global_store_dwordx4 v218, v[108:111], s[90:91] offset:528
	global_load_dwordx4 v[48:51], v221, s[92:93]
	global_load_dwordx4 v[52:55], v221, s[92:93] offset:16
	global_load_dwordx4 v[56:59], v221, s[92:93] offset:512
	global_load_dwordx4 v[60:63], v221, s[92:93] offset:528
	s_waitcnt vmcnt(16)
	s_nop 0
	v_pk_fma_f32 v[80:81], v[44:45], v[198:199], v[80:81]
	v_pk_fma_f32 v[82:83], v[46:47], v[200:201], v[82:83]
	v_pk_fma_f32 v[84:85], v[36:37], v[202:203], v[84:85]
	v_pk_fma_f32 v[86:87], v[38:39], v[204:205], v[86:87]
	v_pk_fma_f32 v[88:89], v[40:41], v[206:207], v[88:89]
	v_pk_fma_f32 v[90:91], v[42:43], v[208:209], v[90:91]
	v_pk_fma_f32 v[92:93], v[32:33], v[210:211], v[92:93]
	v_pk_fma_f32 v[94:95], v[34:35], v[212:213], v[94:95]
	global_store_dwordx4 v219, v[80:83], s[90:91]
	global_store_dwordx4 v219, v[84:87], s[90:91] offset:16
	global_store_dwordx4 v219, v[88:91], s[90:91] offset:512
	global_store_dwordx4 v219, v[92:95], s[90:91] offset:528
	s_waitcnt vmcnt(12)
	s_nop 0
	v_pk_fma_f32 v[64:65], v[28:29], v[198:199], v[64:65]
	v_pk_fma_f32 v[66:67], v[30:31], v[200:201], v[66:67]
	v_pk_fma_f32 v[68:69], v[20:21], v[202:203], v[68:69]
	v_pk_fma_f32 v[70:71], v[22:23], v[204:205], v[70:71]
	v_pk_fma_f32 v[72:73], v[24:25], v[206:207], v[72:73]
	v_pk_fma_f32 v[74:75], v[26:27], v[208:209], v[74:75]
	v_pk_fma_f32 v[76:77], v[16:17], v[210:211], v[76:77]
	v_pk_fma_f32 v[78:79], v[18:19], v[212:213], v[78:79]
	global_store_dwordx4 v220, v[64:67], s[90:91]
	global_store_dwordx4 v220, v[68:71], s[90:91] offset:16
	global_store_dwordx4 v220, v[72:75], s[90:91] offset:512
	global_store_dwordx4 v220, v[76:79], s[90:91] offset:528
	s_waitcnt vmcnt(8)
	s_nop 0
	v_pk_fma_f32 v[48:49], v[12:13], v[198:199], v[48:49]
	v_pk_fma_f32 v[50:51], v[14:15], v[200:201], v[50:51]
	v_pk_fma_f32 v[52:53], v[4:5], v[202:203], v[52:53]
	v_pk_fma_f32 v[54:55], v[6:7], v[204:205], v[54:55]
	v_pk_fma_f32 v[56:57], v[8:9], v[206:207], v[56:57]
	v_pk_fma_f32 v[58:59], v[10:11], v[208:209], v[58:59]
	v_pk_fma_f32 v[60:61], v[0:1], v[210:211], v[60:61]
	v_pk_fma_f32 v[62:63], v[2:3], v[212:213], v[62:63]
	global_store_dwordx4 v221, v[48:51], s[90:91]
	global_store_dwordx4 v221, v[52:55], s[90:91] offset:16
	global_store_dwordx4 v221, v[56:59], s[90:91] offset:512
	global_store_dwordx4 v221, v[60:63], s[90:91] offset:528

.LBB0_226:
	s_andn2_b64 vcc, exec, s[0:1]
	s_cbranch_vccnz .LBB0_133
	s_nop 0
	v_lshl_or_b32 v130, s18, 7, v238
	v_mad_u32_u24 v130, v196, s75, v130
	v_mov_b32_e32 v146, 0xbfb8aa3b
	v_lshlrev_b32_e64 v130, 1, v130
	v_pk_mul_f32 v[142:143], v[124:125], v[146:147] op_sel_hi:[1,0]
	v_pk_mul_f32 v[144:145], v[126:127], v[146:147] op_sel_hi:[1,0]
	v_exp_f32_e64 v142, v142
	v_exp_f32_e64 v143, v143
	v_exp_f32_e64 v144, v144
	v_exp_f32_e64 v145, v145
	v_pk_add_f32 v[142:143], v[142:143], 1.0 op_sel_hi:[1,0]
	v_pk_add_f32 v[144:145], v[144:145], 1.0 op_sel_hi:[1,0]
	v_rcp_f32_e64 v142, v142
	v_rcp_f32_e64 v143, v143
	v_rcp_f32_e64 v144, v144
	v_rcp_f32_e64 v145, v145
	v_pk_mul_f32 v[124:125], v[124:125], v[142:143]
	v_pk_mul_f32 v[126:127], v[126:127], v[144:145]
	v_pk_mul_f32 v[124:125], v[124:125], v[120:121]
	v_pk_mul_f32 v[126:127], v[126:127], v[122:123]
	v_pk_mul_f32 v[142:143], v[116:117], v[146:147] op_sel_hi:[1,0]
	v_pk_mul_f32 v[144:145], v[118:119], v[146:147] op_sel_hi:[1,0]
	v_exp_f32_e64 v142, v142
	v_exp_f32_e64 v143, v143
	v_exp_f32_e64 v144, v144
	v_exp_f32_e64 v145, v145
	v_pk_add_f32 v[142:143], v[142:143], 1.0 op_sel_hi:[1,0]
	v_pk_add_f32 v[144:145], v[144:145], 1.0 op_sel_hi:[1,0]
	v_rcp_f32_e64 v142, v142
	v_rcp_f32_e64 v143, v143
	v_rcp_f32_e64 v144, v144
	v_rcp_f32_e64 v145, v145
	v_pk_mul_f32 v[116:117], v[116:117], v[142:143]
	v_pk_mul_f32 v[118:119], v[118:119], v[144:145]
	v_pk_mul_f32 v[116:117], v[116:117], v[112:113]
	v_pk_mul_f32 v[118:119], v[118:119], v[114:115]
	v_cvt_pk_bf16_f32 v112, v124, v125
	v_cvt_pk_bf16_f32 v113, v126, v127
	v_cvt_pk_bf16_f32 v114, v116, v117
	v_cvt_pk_bf16_f32 v115, v118, v119
	global_store_dwordx4 v130, v[112:115], s[86:87]
	v_add_u32_e32 v130, 0x16000, v130
	v_pk_mul_f32 v[142:143], v[108:109], v[146:147] op_sel_hi:[1,0]
	v_pk_mul_f32 v[144:145], v[110:111], v[146:147] op_sel_hi:[1,0]
	v_exp_f32_e64 v142, v142
	v_exp_f32_e64 v143, v143
	v_exp_f32_e64 v144, v144
	v_exp_f32_e64 v145, v145
	v_pk_add_f32 v[142:143], v[142:143], 1.0 op_sel_hi:[1,0]
	v_pk_add_f32 v[144:145], v[144:145], 1.0 op_sel_hi:[1,0]
	v_rcp_f32_e64 v142, v142
	v_rcp_f32_e64 v143, v143
	v_rcp_f32_e64 v144, v144
	v_rcp_f32_e64 v145, v145
	v_pk_mul_f32 v[108:109], v[108:109], v[142:143]
	v_pk_mul_f32 v[110:111], v[110:111], v[144:145]
	v_pk_mul_f32 v[108:109], v[108:109], v[104:105]
	v_pk_mul_f32 v[110:111], v[110:111], v[106:107]
	v_pk_mul_f32 v[142:143], v[100:101], v[146:147] op_sel_hi:[1,0]
	v_pk_mul_f32 v[144:145], v[102:103], v[146:147] op_sel_hi:[1,0]
	v_exp_f32_e64 v142, v142
	v_exp_f32_e64 v143, v143
	v_exp_f32_e64 v144, v144
	v_exp_f32_e64 v145, v145
	v_pk_add_f32 v[142:143], v[142:143], 1.0 op_sel_hi:[1,0]
	v_pk_add_f32 v[144:145], v[144:145], 1.0 op_sel_hi:[1,0]
	v_rcp_f32_e64 v142, v142
	v_rcp_f32_e64 v143, v143
	v_rcp_f32_e64 v144, v144
	v_rcp_f32_e64 v145, v145
	v_pk_mul_f32 v[100:101], v[100:101], v[142:143]
	v_pk_mul_f32 v[102:103], v[102:103], v[144:145]
	v_pk_mul_f32 v[100:101], v[100:101], v[96:97]
	v_pk_mul_f32 v[102:103], v[102:103], v[98:99]
	v_cvt_pk_bf16_f32 v96, v108, v109
	v_cvt_pk_bf16_f32 v97, v110, v111
	v_cvt_pk_bf16_f32 v98, v100, v101
	v_cvt_pk_bf16_f32 v99, v102, v103
	global_store_dwordx4 v130, v[96:99], s[86:87]
	v_add_u32_e32 v130, 0x16000, v130
	v_pk_mul_f32 v[142:143], v[92:93], v[146:147] op_sel_hi:[1,0]
	v_pk_mul_f32 v[144:145], v[94:95], v[146:147] op_sel_hi:[1,0]
	v_exp_f32_e64 v142, v142
	v_exp_f32_e64 v143, v143
	v_exp_f32_e64 v144, v144
	v_exp_f32_e64 v145, v145
	v_pk_add_f32 v[142:143], v[142:143], 1.0 op_sel_hi:[1,0]
	v_pk_add_f32 v[144:145], v[144:145], 1.0 op_sel_hi:[1,0]
	v_rcp_f32_e64 v142, v142
	v_rcp_f32_e64 v143, v143
	v_rcp_f32_e64 v144, v144
	v_rcp_f32_e64 v145, v145
	v_pk_mul_f32 v[92:93], v[92:93], v[142:143]
	v_pk_mul_f32 v[94:95], v[94:95], v[144:145]
	v_pk_mul_f32 v[92:93], v[92:93], v[88:89]
	v_pk_mul_f32 v[94:95], v[94:95], v[90:91]
	v_pk_mul_f32 v[142:143], v[84:85], v[146:147] op_sel_hi:[1,0]
	v_pk_mul_f32 v[144:145], v[86:87], v[146:147] op_sel_hi:[1,0]
	v_exp_f32_e64 v142, v142
	v_exp_f32_e64 v143, v143
	v_exp_f32_e64 v144, v144
	v_exp_f32_e64 v145, v145
	v_pk_add_f32 v[142:143], v[142:143], 1.0 op_sel_hi:[1,0]
	v_pk_add_f32 v[144:145], v[144:145], 1.0 op_sel_hi:[1,0]
	v_rcp_f32_e64 v142, v142
	v_rcp_f32_e64 v143, v143
	v_rcp_f32_e64 v144, v144
	v_rcp_f32_e64 v145, v145
	v_pk_mul_f32 v[84:85], v[84:85], v[142:143]
	v_pk_mul_f32 v[86:87], v[86:87], v[144:145]
	v_pk_mul_f32 v[84:85], v[84:85], v[80:81]
	v_pk_mul_f32 v[86:87], v[86:87], v[82:83]
	v_cvt_pk_bf16_f32 v80, v92, v93
	v_cvt_pk_bf16_f32 v81, v94, v95
	v_cvt_pk_bf16_f32 v82, v84, v85
	v_cvt_pk_bf16_f32 v83, v86, v87
	global_store_dwordx4 v130, v[80:83], s[86:87]
	v_add_u32_e32 v130, 0x16000, v130
	v_pk_mul_f32 v[142:143], v[76:77], v[146:147] op_sel_hi:[1,0]
	v_pk_mul_f32 v[144:145], v[78:79], v[146:147] op_sel_hi:[1,0]
	v_exp_f32_e64 v142, v142
	v_exp_f32_e64 v143, v143
	v_exp_f32_e64 v144, v144
	v_exp_f32_e64 v145, v145
	v_pk_add_f32 v[142:143], v[142:143], 1.0 op_sel_hi:[1,0]
	v_pk_add_f32 v[144:145], v[144:145], 1.0 op_sel_hi:[1,0]
	v_rcp_f32_e64 v142, v142
	v_rcp_f32_e64 v143, v143
	v_rcp_f32_e64 v144, v144
	v_rcp_f32_e64 v145, v145
	v_pk_mul_f32 v[76:77], v[76:77], v[142:143]
	v_pk_mul_f32 v[78:79], v[78:79], v[144:145]
	v_pk_mul_f32 v[76:77], v[76:77], v[72:73]
	v_pk_mul_f32 v[78:79], v[78:79], v[74:75]
	v_pk_mul_f32 v[142:143], v[68:69], v[146:147] op_sel_hi:[1,0]
	v_pk_mul_f32 v[144:145], v[70:71], v[146:147] op_sel_hi:[1,0]
	v_exp_f32_e64 v142, v142
	v_exp_f32_e64 v143, v143
	v_exp_f32_e64 v144, v144
	v_exp_f32_e64 v145, v145
	v_pk_add_f32 v[142:143], v[142:143], 1.0 op_sel_hi:[1,0]
	v_pk_add_f32 v[144:145], v[144:145], 1.0 op_sel_hi:[1,0]
	v_rcp_f32_e64 v142, v142
	v_rcp_f32_e64 v143, v143
	v_rcp_f32_e64 v144, v144
	v_rcp_f32_e64 v145, v145
	v_pk_mul_f32 v[68:69], v[68:69], v[142:143]
	v_pk_mul_f32 v[70:71], v[70:71], v[144:145]
	v_pk_mul_f32 v[68:69], v[68:69], v[64:65]
	v_pk_mul_f32 v[70:71], v[70:71], v[66:67]
	v_cvt_pk_bf16_f32 v64, v76, v77
	v_cvt_pk_bf16_f32 v65, v78, v79
	v_cvt_pk_bf16_f32 v66, v68, v69
	v_cvt_pk_bf16_f32 v67, v70, v71
	global_store_dwordx4 v130, v[64:67], s[86:87]
	v_add_u32_e32 v130, 0x6e000, v130
	v_pk_mul_f32 v[142:143], v[60:61], v[146:147] op_sel_hi:[1,0]
	v_pk_mul_f32 v[144:145], v[62:63], v[146:147] op_sel_hi:[1,0]
	v_exp_f32_e64 v142, v142
	v_exp_f32_e64 v143, v143
	v_exp_f32_e64 v144, v144
	v_exp_f32_e64 v145, v145
	v_pk_add_f32 v[142:143], v[142:143], 1.0 op_sel_hi:[1,0]
	v_pk_add_f32 v[144:145], v[144:145], 1.0 op_sel_hi:[1,0]
	v_rcp_f32_e64 v142, v142
	v_rcp_f32_e64 v143, v143
	v_rcp_f32_e64 v144, v144
	v_rcp_f32_e64 v145, v145
	v_pk_mul_f32 v[60:61], v[60:61], v[142:143]
	v_pk_mul_f32 v[62:63], v[62:63], v[144:145]
	v_pk_mul_f32 v[60:61], v[60:61], v[56:57]
	v_pk_mul_f32 v[62:63], v[62:63], v[58:59]
	v_pk_mul_f32 v[142:143], v[52:53], v[146:147] op_sel_hi:[1,0]
	v_pk_mul_f32 v[144:145], v[54:55], v[146:147] op_sel_hi:[1,0]
	v_exp_f32_e64 v142, v142
	v_exp_f32_e64 v143, v143
	v_exp_f32_e64 v144, v144
	v_exp_f32_e64 v145, v145
	v_pk_add_f32 v[142:143], v[142:143], 1.0 op_sel_hi:[1,0]
	v_pk_add_f32 v[144:145], v[144:145], 1.0 op_sel_hi:[1,0]
	v_rcp_f32_e64 v142, v142
	v_rcp_f32_e64 v143, v143
	v_rcp_f32_e64 v144, v144
	v_rcp_f32_e64 v145, v145
	v_pk_mul_f32 v[52:53], v[52:53], v[142:143]
	v_pk_mul_f32 v[54:55], v[54:55], v[144:145]
	v_pk_mul_f32 v[52:53], v[52:53], v[48:49]
	v_pk_mul_f32 v[54:55], v[54:55], v[50:51]
	v_cvt_pk_bf16_f32 v48, v60, v61
	v_cvt_pk_bf16_f32 v49, v62, v63
	v_cvt_pk_bf16_f32 v50, v52, v53
	v_cvt_pk_bf16_f32 v51, v54, v55
	global_store_dwordx4 v130, v[48:51], s[86:87]
	v_add_u32_e32 v130, 0x16000, v130
	v_pk_mul_f32 v[142:143], v[44:45], v[146:147] op_sel_hi:[1,0]
	v_pk_mul_f32 v[144:145], v[46:47], v[146:147] op_sel_hi:[1,0]
	v_exp_f32_e64 v142, v142
	v_exp_f32_e64 v143, v143
	v_exp_f32_e64 v144, v144
	v_exp_f32_e64 v145, v145
	v_pk_add_f32 v[142:143], v[142:143], 1.0 op_sel_hi:[1,0]
	v_pk_add_f32 v[144:145], v[144:145], 1.0 op_sel_hi:[1,0]
	v_rcp_f32_e64 v142, v142
	v_rcp_f32_e64 v143, v143
	v_rcp_f32_e64 v144, v144
	v_rcp_f32_e64 v145, v145
	v_pk_mul_f32 v[44:45], v[44:45], v[142:143]
	v_pk_mul_f32 v[46:47], v[46:47], v[144:145]
	v_pk_mul_f32 v[44:45], v[44:45], v[40:41]
	v_pk_mul_f32 v[46:47], v[46:47], v[42:43]
	v_pk_mul_f32 v[142:143], v[36:37], v[146:147] op_sel_hi:[1,0]
	v_pk_mul_f32 v[144:145], v[38:39], v[146:147] op_sel_hi:[1,0]
	v_exp_f32_e64 v142, v142
	v_exp_f32_e64 v143, v143
	v_exp_f32_e64 v144, v144
	v_exp_f32_e64 v145, v145
	v_pk_add_f32 v[142:143], v[142:143], 1.0 op_sel_hi:[1,0]
	v_pk_add_f32 v[144:145], v[144:145], 1.0 op_sel_hi:[1,0]
	v_rcp_f32_e64 v142, v142
	v_rcp_f32_e64 v143, v143
	v_rcp_f32_e64 v144, v144
	v_rcp_f32_e64 v145, v145
	v_pk_mul_f32 v[36:37], v[36:37], v[142:143]
	v_pk_mul_f32 v[38:39], v[38:39], v[144:145]
	v_pk_mul_f32 v[36:37], v[36:37], v[32:33]
	v_pk_mul_f32 v[38:39], v[38:39], v[34:35]
	v_cvt_pk_bf16_f32 v32, v44, v45
	v_cvt_pk_bf16_f32 v33, v46, v47
	v_cvt_pk_bf16_f32 v34, v36, v37
	v_cvt_pk_bf16_f32 v35, v38, v39
	global_store_dwordx4 v130, v[32:35], s[86:87]
	v_add_u32_e32 v130, 0x16000, v130
	v_pk_mul_f32 v[142:143], v[28:29], v[146:147] op_sel_hi:[1,0]
	v_pk_mul_f32 v[144:145], v[30:31], v[146:147] op_sel_hi:[1,0]
	v_exp_f32_e64 v142, v142
	v_exp_f32_e64 v143, v143
	v_exp_f32_e64 v144, v144
	v_exp_f32_e64 v145, v145
	v_pk_add_f32 v[142:143], v[142:143], 1.0 op_sel_hi:[1,0]
	v_pk_add_f32 v[144:145], v[144:145], 1.0 op_sel_hi:[1,0]
	v_rcp_f32_e64 v142, v142
	v_rcp_f32_e64 v143, v143
	v_rcp_f32_e64 v144, v144
	v_rcp_f32_e64 v145, v145
	v_pk_mul_f32 v[28:29], v[28:29], v[142:143]
	v_pk_mul_f32 v[30:31], v[30:31], v[144:145]
	v_pk_mul_f32 v[28:29], v[28:29], v[24:25]
	v_pk_mul_f32 v[30:31], v[30:31], v[26:27]
	v_pk_mul_f32 v[142:143], v[20:21], v[146:147] op_sel_hi:[1,0]
	v_pk_mul_f32 v[144:145], v[22:23], v[146:147] op_sel_hi:[1,0]
	v_exp_f32_e64 v142, v142
	v_exp_f32_e64 v143, v143
	v_exp_f32_e64 v144, v144
	v_exp_f32_e64 v145, v145
	v_pk_add_f32 v[142:143], v[142:143], 1.0 op_sel_hi:[1,0]
	v_pk_add_f32 v[144:145], v[144:145], 1.0 op_sel_hi:[1,0]
	v_rcp_f32_e64 v142, v142
	v_rcp_f32_e64 v143, v143
	v_rcp_f32_e64 v144, v144
	v_rcp_f32_e64 v145, v145
	v_pk_mul_f32 v[20:21], v[20:21], v[142:143]
	v_pk_mul_f32 v[22:23], v[22:23], v[144:145]
	v_pk_mul_f32 v[20:21], v[20:21], v[16:17]
	v_pk_mul_f32 v[22:23], v[22:23], v[18:19]
	v_cvt_pk_bf16_f32 v16, v28, v29
	v_cvt_pk_bf16_f32 v17, v30, v31
	v_cvt_pk_bf16_f32 v18, v20, v21
	v_cvt_pk_bf16_f32 v19, v22, v23
	global_store_dwordx4 v130, v[16:19], s[86:87]
	v_add_u32_e32 v130, 0x16000, v130
	v_pk_mul_f32 v[142:143], v[12:13], v[146:147] op_sel_hi:[1,0]
	v_pk_mul_f32 v[144:145], v[14:15], v[146:147] op_sel_hi:[1,0]
	v_exp_f32_e64 v142, v142
	v_exp_f32_e64 v143, v143
	v_exp_f32_e64 v144, v144
	v_exp_f32_e64 v145, v145
	v_pk_add_f32 v[142:143], v[142:143], 1.0 op_sel_hi:[1,0]
	v_pk_add_f32 v[144:145], v[144:145], 1.0 op_sel_hi:[1,0]
	v_rcp_f32_e64 v142, v142
	v_rcp_f32_e64 v143, v143
	v_rcp_f32_e64 v144, v144
	v_rcp_f32_e64 v145, v145
	v_pk_mul_f32 v[12:13], v[12:13], v[142:143]
	v_pk_mul_f32 v[14:15], v[14:15], v[144:145]
	v_pk_mul_f32 v[12:13], v[12:13], v[8:9]
	v_pk_mul_f32 v[14:15], v[14:15], v[10:11]
	v_pk_mul_f32 v[142:143], v[4:5], v[146:147] op_sel_hi:[1,0]
	v_pk_mul_f32 v[144:145], v[6:7], v[146:147] op_sel_hi:[1,0]
	v_exp_f32_e64 v142, v142
	v_exp_f32_e64 v143, v143
	v_exp_f32_e64 v144, v144
	v_exp_f32_e64 v145, v145
	v_pk_add_f32 v[142:143], v[142:143], 1.0 op_sel_hi:[1,0]
	v_pk_add_f32 v[144:145], v[144:145], 1.0 op_sel_hi:[1,0]
	v_rcp_f32_e64 v142, v142
	v_rcp_f32_e64 v143, v143
	v_rcp_f32_e64 v144, v144
	v_rcp_f32_e64 v145, v145
	v_pk_mul_f32 v[4:5], v[4:5], v[142:143]
	v_pk_mul_f32 v[6:7], v[6:7], v[144:145]
	v_pk_mul_f32 v[4:5], v[4:5], v[0:1]
	v_pk_mul_f32 v[6:7], v[6:7], v[2:3]
	v_cvt_pk_bf16_f32 v0, v12, v13
	v_cvt_pk_bf16_f32 v1, v14, v15
	v_cvt_pk_bf16_f32 v2, v4, v5
	v_cvt_pk_bf16_f32 v3, v6, v7
	global_store_dwordx4 v130, v[0:3], s[86:87]
	s_branch .LBB0_133
